# in-proj and out-proj GEMM main loops fully unrolled: compile-time LDS stages, fragment-read addresses are register+immediate (no per-step VALU address adds, no loop control)
# speedup vs baseline: 1.0128x; 1.0128x over previous
.LBB0_213:
	s_andn2_b64 vcc, exec, s[6:7]
	s_mov_b64 s[6:7], 0
	s_cbranch_vccnz .LBB0_209
	s_ashr_i32 s39, s38, 31
	s_lshl_b64 s[6:7], s[38:39], 18
	s_add_u32 s72, s3, s6
	s_addc_u32 s73, s33, s7
	s_ashr_i32 s11, s10, 31
	s_lshl_b64 s[34:35], s[10:11], 19
	s_add_u32 s74, s50, s34
	s_addc_u32 s75, s51, s35
	v_readfirstlane_b32 s11, v184
	s_nop 3
	s_lshr_b32 s0, s11, 6
	s_lshr_b32 s39, s11, 4
	s_and_b32 s39, s39, 4
	v_lshl_or_b32 v2, s0, 3, v210
	v_bitop3_b32 v8, s39, v208, v209 bitop3:0x36
	v_lshlrev_b32_e32 v2, 11, v2
	v_lshlrev_b32_e32 v8, 4, v8
	v_or_b32_e32 v144, v2, v8
	v_add_u32_e32 v145, 0x20000, v144
	v_add_u32_e32 v146, 0x40000, v144
	v_add_u32_e32 v147, 0x60000, v144
	s_lshl_b32 s79, s0, 10
	s_lshr_b32 s9, s11, 1
	s_and_b32 s9, s9, 0x1ffffc0
	v_and_or_b32 v4, s11, 64, v189
	v_lshlrev_b32_e32 v106, 7, v4
	v_or_b32_e32 v4, s9, v189
	v_lshlrev_b32_e32 v107, 7, v4
	s_add_i32 m0, s79, 0x100
	s_nop 0
	global_load_lds_dwordx4 v144, s[72:73]
	s_add_i32 m0, s79, 0x2100
	s_nop 0
	global_load_lds_dwordx4 v145, s[72:73]
	s_add_i32 m0, s79, 0x4100
	s_nop 0
	global_load_lds_dwordx4 v144, s[74:75]
	s_add_i32 m0, s79, 0x6100
	s_nop 0
	global_load_lds_dwordx4 v145, s[74:75]
	s_add_i32 m0, s79, 0x8100
	s_nop 0
	global_load_lds_dwordx4 v146, s[74:75]
	s_add_i32 m0, s79, 0xa100
	s_nop 0
	global_load_lds_dwordx4 v147, s[74:75]
	s_add_u32 s72, s72, 0x80
	s_addc_u32 s73, s73, 0
	s_add_u32 s74, s74, 0x80
	s_addc_u32 s75, s75, 0
	s_add_i32 m0, s79, 0xc100
	s_nop 0
	global_load_lds_dwordx4 v144, s[72:73]
	s_add_i32 m0, s79, 0xe100
	s_nop 0
	global_load_lds_dwordx4 v145, s[72:73]
	s_add_i32 m0, s79, 0x10100
	s_nop 0
	global_load_lds_dwordx4 v144, s[74:75]
	s_add_i32 m0, s79, 0x12100
	s_nop 0
	global_load_lds_dwordx4 v145, s[74:75]
	s_add_i32 m0, s79, 0x14100
	s_nop 0
	global_load_lds_dwordx4 v146, s[74:75]
	s_add_i32 m0, s79, 0x16100
	s_nop 0
	global_load_lds_dwordx4 v147, s[74:75]
	s_add_u32 s72, s72, 0x80
	s_addc_u32 s73, s73, 0
	s_add_u32 s74, s74, 0x80
	s_addc_u32 s75, s75, 0
	v_mov_b32_e32 v50, 0
	v_mov_b32_e32 v51, 0
	v_mov_b32_e32 v52, 0
	v_mov_b32_e32 v53, 0
	v_mov_b32_e32 v54, 0
	v_mov_b32_e32 v55, 0
	v_mov_b32_e32 v56, 0
	v_mov_b32_e32 v57, 0
	v_mov_b32_e32 v58, 0
	v_mov_b32_e32 v59, 0
	v_mov_b32_e32 v60, 0
	v_mov_b32_e32 v61, 0
	v_mov_b32_e32 v62, 0
	v_mov_b32_e32 v63, 0
	v_mov_b32_e32 v64, 0
	v_mov_b32_e32 v65, 0
	v_mov_b32_e32 v18, 0
	v_mov_b32_e32 v19, 0
	v_mov_b32_e32 v20, 0
	v_mov_b32_e32 v21, 0
	v_mov_b32_e32 v22, 0
	v_mov_b32_e32 v23, 0
	v_mov_b32_e32 v24, 0
	v_mov_b32_e32 v25, 0
	v_mov_b32_e32 v26, 0
	v_mov_b32_e32 v27, 0
	v_mov_b32_e32 v28, 0
	v_mov_b32_e32 v29, 0
	v_mov_b32_e32 v30, 0
	v_mov_b32_e32 v31, 0
	v_mov_b32_e32 v32, 0
	v_mov_b32_e32 v33, 0
	v_mov_b32_e32 v34, 0
	v_mov_b32_e32 v35, 0
	v_mov_b32_e32 v36, 0
	v_mov_b32_e32 v37, 0
	v_mov_b32_e32 v38, 0
	v_mov_b32_e32 v39, 0
	v_mov_b32_e32 v40, 0
	v_mov_b32_e32 v41, 0
	v_mov_b32_e32 v42, 0
	v_mov_b32_e32 v43, 0
	v_mov_b32_e32 v44, 0
	v_mov_b32_e32 v45, 0
	v_mov_b32_e32 v46, 0
	v_mov_b32_e32 v47, 0
	v_mov_b32_e32 v48, 0
	v_mov_b32_e32 v49, 0
	v_mov_b32_e32 v2, 0
	v_mov_b32_e32 v3, 0
	v_mov_b32_e32 v4, 0
	v_mov_b32_e32 v5, 0
	v_mov_b32_e32 v6, 0
	v_mov_b32_e32 v7, 0
	v_mov_b32_e32 v8, 0
	v_mov_b32_e32 v9, 0
	v_mov_b32_e32 v10, 0
	v_mov_b32_e32 v11, 0
	v_mov_b32_e32 v12, 0
	v_mov_b32_e32 v13, 0
	v_mov_b32_e32 v14, 0
	v_mov_b32_e32 v15, 0
	v_mov_b32_e32 v16, 0
	v_mov_b32_e32 v17, 0
	s_movk_i32 s81, 0x100
	v_add3_u32 v216, s81, v106, v211
	v_add3_u32 v217, s81, v106, v212
	v_add3_u32 v218, s81, v106, v213
	v_add3_u32 v219, s81, v106, v214
	s_movk_i32 s81, 0x4100
	v_add3_u32 v220, s81, v107, v211
	v_add3_u32 v221, s81, v107, v212
	v_add3_u32 v222, s81, v107, v213
	v_add3_u32 v223, s81, v107, v214
	s_mov_b32 s81, 0x1b800
	v_add_u32_e32 v224, s81, v216
	v_add_u32_e32 v228, s81, v220
	v_add_u32_e32 v225, s81, v217
	v_add_u32_e32 v229, s81, v221
	v_add_u32_e32 v226, s81, v218
	v_add_u32_e32 v230, s81, v222
	v_add_u32_e32 v227, s81, v219
	v_add_u32_e32 v231, s81, v223
	s_waitcnt vmcnt(6)
	s_barrier
	ds_read_b128 v[108:111], v216
	ds_read_b128 v[116:119], v220
	ds_read_b128 v[120:123], v220 offset:4096
	ds_read_b128 v[112:115], v216 offset:4096
.Lg1_loop:
	s_add_i32 m0, s79, 0x1b900
	s_nop 0
	global_load_lds_dwordx4 v144, s[72:73]
	s_add_i32 m0, s79, 0x1d900
	s_nop 0
	global_load_lds_dwordx4 v145, s[72:73]
	s_add_i32 m0, s79, 0x1f900
	s_nop 0
	global_load_lds_dwordx4 v144, s[74:75]
	s_add_i32 m0, s79, 0x21900
	s_nop 0
	global_load_lds_dwordx4 v145, s[74:75]
	s_add_i32 m0, s79, 0x23900
	s_nop 0
	global_load_lds_dwordx4 v146, s[74:75]
	s_add_i32 m0, s79, 0x25900
	s_nop 0
	global_load_lds_dwordx4 v147, s[74:75]
	s_add_u32 s72, s72, 0x80
	s_addc_u32 s73, s73, 0
	s_add_u32 s74, s74, 0x80
	s_addc_u32 s75, s75, 0
	ds_read_b128 v[126:129], v217
	ds_read_b128 v[134:137], v221
	ds_read_b128 v[138:141], v221 offset:4096
	ds_read_b128 v[130:133], v217 offset:4096
	s_setprio 1
	s_waitcnt lgkmcnt(6)
	v_mfma_f32_32x32x16_bf16 v[50:65], v[108:111], v[116:119], v[50:65]
	s_waitcnt lgkmcnt(5)
	v_mfma_f32_32x32x16_bf16 v[18:33], v[108:111], v[120:123], v[18:33]
	s_waitcnt lgkmcnt(4)
	v_mfma_f32_32x32x16_bf16 v[34:49], v[112:115], v[116:119], v[34:49]
	v_mfma_f32_32x32x16_bf16 v[2:17], v[112:115], v[120:123], v[2:17]
	s_setprio 0
	ds_read_b128 v[108:111], v218
	ds_read_b128 v[116:119], v222
	ds_read_b128 v[120:123], v222 offset:4096
	ds_read_b128 v[112:115], v218 offset:4096
	s_setprio 1
	s_waitcnt lgkmcnt(6)
	v_mfma_f32_32x32x16_bf16 v[50:65], v[126:129], v[134:137], v[50:65]
	s_waitcnt lgkmcnt(5)
	v_mfma_f32_32x32x16_bf16 v[18:33], v[126:129], v[138:141], v[18:33]
	s_waitcnt lgkmcnt(4)
	v_mfma_f32_32x32x16_bf16 v[34:49], v[130:133], v[134:137], v[34:49]
	v_mfma_f32_32x32x16_bf16 v[2:17], v[130:133], v[138:141], v[2:17]
	s_setprio 0
	ds_read_b128 v[126:129], v219
	ds_read_b128 v[134:137], v223
	ds_read_b128 v[138:141], v223 offset:4096
	ds_read_b128 v[130:133], v219 offset:4096
	s_setprio 1
	s_waitcnt lgkmcnt(6)
	v_mfma_f32_32x32x16_bf16 v[50:65], v[108:111], v[116:119], v[50:65]
	s_waitcnt lgkmcnt(5)
	v_mfma_f32_32x32x16_bf16 v[18:33], v[108:111], v[120:123], v[18:33]
	s_waitcnt lgkmcnt(4)
	v_mfma_f32_32x32x16_bf16 v[34:49], v[112:115], v[116:119], v[34:49]
	v_mfma_f32_32x32x16_bf16 v[2:17], v[112:115], v[120:123], v[2:17]
	s_setprio 0
	s_waitcnt lgkmcnt(0)
	s_waitcnt vmcnt(6)
	s_barrier
	ds_read_b128 v[108:111], v216 offset:49152
	ds_read_b128 v[116:119], v220 offset:49152
	ds_read_b128 v[120:123], v220 offset:53248
	ds_read_b128 v[112:115], v216 offset:53248
	s_setprio 1
	v_mfma_f32_32x32x16_bf16 v[50:65], v[126:129], v[134:137], v[50:65]
	v_mfma_f32_32x32x16_bf16 v[18:33], v[126:129], v[138:141], v[18:33]
	v_mfma_f32_32x32x16_bf16 v[34:49], v[130:133], v[134:137], v[34:49]
	v_mfma_f32_32x32x16_bf16 v[2:17], v[130:133], v[138:141], v[2:17]
	s_setprio 0
	s_add_i32 m0, s79, 0x100
	s_nop 0
	global_load_lds_dwordx4 v144, s[72:73]
	s_add_i32 m0, s79, 0x2100
	s_nop 0
	global_load_lds_dwordx4 v145, s[72:73]
	s_add_i32 m0, s79, 0x4100
	s_nop 0
	global_load_lds_dwordx4 v144, s[74:75]
	s_add_i32 m0, s79, 0x6100
	s_nop 0
	global_load_lds_dwordx4 v145, s[74:75]
	s_add_i32 m0, s79, 0x8100
	s_nop 0
	global_load_lds_dwordx4 v146, s[74:75]
	s_add_i32 m0, s79, 0xa100
	s_nop 0
	global_load_lds_dwordx4 v147, s[74:75]
	s_add_u32 s72, s72, 0x80
	s_addc_u32 s73, s73, 0
	s_add_u32 s74, s74, 0x80
	s_addc_u32 s75, s75, 0
	ds_read_b128 v[126:129], v217 offset:49152
	ds_read_b128 v[134:137], v221 offset:49152
	ds_read_b128 v[138:141], v221 offset:53248
	ds_read_b128 v[130:133], v217 offset:53248
	s_setprio 1
	s_waitcnt lgkmcnt(6)
	v_mfma_f32_32x32x16_bf16 v[50:65], v[108:111], v[116:119], v[50:65]
	s_waitcnt lgkmcnt(5)
	v_mfma_f32_32x32x16_bf16 v[18:33], v[108:111], v[120:123], v[18:33]
	s_waitcnt lgkmcnt(4)
	v_mfma_f32_32x32x16_bf16 v[34:49], v[112:115], v[116:119], v[34:49]
	v_mfma_f32_32x32x16_bf16 v[2:17], v[112:115], v[120:123], v[2:17]
	s_setprio 0
	ds_read_b128 v[108:111], v218 offset:49152
	ds_read_b128 v[116:119], v222 offset:49152
	ds_read_b128 v[120:123], v222 offset:53248
	ds_read_b128 v[112:115], v218 offset:53248
	s_setprio 1
	s_waitcnt lgkmcnt(6)
	v_mfma_f32_32x32x16_bf16 v[50:65], v[126:129], v[134:137], v[50:65]
	s_waitcnt lgkmcnt(5)
	v_mfma_f32_32x32x16_bf16 v[18:33], v[126:129], v[138:141], v[18:33]
	s_waitcnt lgkmcnt(4)
	v_mfma_f32_32x32x16_bf16 v[34:49], v[130:133], v[134:137], v[34:49]
	v_mfma_f32_32x32x16_bf16 v[2:17], v[130:133], v[138:141], v[2:17]
	s_setprio 0
	ds_read_b128 v[126:129], v219 offset:49152
	ds_read_b128 v[134:137], v223 offset:49152
	ds_read_b128 v[138:141], v223 offset:53248
	ds_read_b128 v[130:133], v219 offset:53248
	s_setprio 1
	s_waitcnt lgkmcnt(6)
	v_mfma_f32_32x32x16_bf16 v[50:65], v[108:111], v[116:119], v[50:65]
	s_waitcnt lgkmcnt(5)
	v_mfma_f32_32x32x16_bf16 v[18:33], v[108:111], v[120:123], v[18:33]
	s_waitcnt lgkmcnt(4)
	v_mfma_f32_32x32x16_bf16 v[34:49], v[112:115], v[116:119], v[34:49]
	v_mfma_f32_32x32x16_bf16 v[2:17], v[112:115], v[120:123], v[2:17]
	s_setprio 0
	s_waitcnt lgkmcnt(0)
	s_waitcnt vmcnt(6)
	s_barrier
	ds_read_b128 v[108:111], v224
	ds_read_b128 v[116:119], v228
	ds_read_b128 v[120:123], v228 offset:4096
	ds_read_b128 v[112:115], v224 offset:4096
	s_setprio 1
	v_mfma_f32_32x32x16_bf16 v[50:65], v[126:129], v[134:137], v[50:65]
	v_mfma_f32_32x32x16_bf16 v[18:33], v[126:129], v[138:141], v[18:33]
	v_mfma_f32_32x32x16_bf16 v[34:49], v[130:133], v[134:137], v[34:49]
	v_mfma_f32_32x32x16_bf16 v[2:17], v[130:133], v[138:141], v[2:17]
	s_setprio 0
	s_add_i32 m0, s79, 0xc100
	s_nop 0
	global_load_lds_dwordx4 v144, s[72:73]
	s_add_i32 m0, s79, 0xe100
	s_nop 0
	global_load_lds_dwordx4 v145, s[72:73]
	s_add_i32 m0, s79, 0x10100
	s_nop 0
	global_load_lds_dwordx4 v144, s[74:75]
	s_add_i32 m0, s79, 0x12100
	s_nop 0
	global_load_lds_dwordx4 v145, s[74:75]
	s_add_i32 m0, s79, 0x14100
	s_nop 0
	global_load_lds_dwordx4 v146, s[74:75]
	s_add_i32 m0, s79, 0x16100
	s_nop 0
	global_load_lds_dwordx4 v147, s[74:75]
	s_add_u32 s72, s72, 0x80
	s_addc_u32 s73, s73, 0
	s_add_u32 s74, s74, 0x80
	s_addc_u32 s75, s75, 0
	ds_read_b128 v[126:129], v225
	ds_read_b128 v[134:137], v229
	ds_read_b128 v[138:141], v229 offset:4096
	ds_read_b128 v[130:133], v225 offset:4096
	s_setprio 1
	s_waitcnt lgkmcnt(6)
	v_mfma_f32_32x32x16_bf16 v[50:65], v[108:111], v[116:119], v[50:65]
	s_waitcnt lgkmcnt(5)
	v_mfma_f32_32x32x16_bf16 v[18:33], v[108:111], v[120:123], v[18:33]
	s_waitcnt lgkmcnt(4)
	v_mfma_f32_32x32x16_bf16 v[34:49], v[112:115], v[116:119], v[34:49]
	v_mfma_f32_32x32x16_bf16 v[2:17], v[112:115], v[120:123], v[2:17]
	s_setprio 0
	ds_read_b128 v[108:111], v226
	ds_read_b128 v[116:119], v230
	ds_read_b128 v[120:123], v230 offset:4096
	ds_read_b128 v[112:115], v226 offset:4096
	s_setprio 1
	s_waitcnt lgkmcnt(6)
	v_mfma_f32_32x32x16_bf16 v[50:65], v[126:129], v[134:137], v[50:65]
	s_waitcnt lgkmcnt(5)
	v_mfma_f32_32x32x16_bf16 v[18:33], v[126:129], v[138:141], v[18:33]
	s_waitcnt lgkmcnt(4)
	v_mfma_f32_32x32x16_bf16 v[34:49], v[130:133], v[134:137], v[34:49]
	v_mfma_f32_32x32x16_bf16 v[2:17], v[130:133], v[138:141], v[2:17]
	s_setprio 0
	ds_read_b128 v[126:129], v227
	ds_read_b128 v[134:137], v231
	ds_read_b128 v[138:141], v231 offset:4096
	ds_read_b128 v[130:133], v227 offset:4096
	s_setprio 1
	s_waitcnt lgkmcnt(6)
	v_mfma_f32_32x32x16_bf16 v[50:65], v[108:111], v[116:119], v[50:65]
	s_waitcnt lgkmcnt(5)
	v_mfma_f32_32x32x16_bf16 v[18:33], v[108:111], v[120:123], v[18:33]
	s_waitcnt lgkmcnt(4)
	v_mfma_f32_32x32x16_bf16 v[34:49], v[112:115], v[116:119], v[34:49]
	v_mfma_f32_32x32x16_bf16 v[2:17], v[112:115], v[120:123], v[2:17]
	s_setprio 0
	s_waitcnt lgkmcnt(0)
	s_waitcnt vmcnt(6)
	s_barrier
	ds_read_b128 v[108:111], v216
	ds_read_b128 v[116:119], v220
	ds_read_b128 v[120:123], v220 offset:4096
	ds_read_b128 v[112:115], v216 offset:4096
	s_setprio 1
	v_mfma_f32_32x32x16_bf16 v[50:65], v[126:129], v[134:137], v[50:65]
	v_mfma_f32_32x32x16_bf16 v[18:33], v[126:129], v[138:141], v[18:33]
	v_mfma_f32_32x32x16_bf16 v[34:49], v[130:133], v[134:137], v[34:49]
	v_mfma_f32_32x32x16_bf16 v[2:17], v[130:133], v[138:141], v[2:17]
	s_setprio 0
	s_add_i32 m0, s79, 0x1b900
	s_nop 0
	global_load_lds_dwordx4 v144, s[72:73]
	s_add_i32 m0, s79, 0x1d900
	s_nop 0
	global_load_lds_dwordx4 v145, s[72:73]
	s_add_i32 m0, s79, 0x1f900
	s_nop 0
	global_load_lds_dwordx4 v144, s[74:75]
	s_add_i32 m0, s79, 0x21900
	s_nop 0
	global_load_lds_dwordx4 v145, s[74:75]
	s_add_i32 m0, s79, 0x23900
	s_nop 0
	global_load_lds_dwordx4 v146, s[74:75]
	s_add_i32 m0, s79, 0x25900
	s_nop 0
	global_load_lds_dwordx4 v147, s[74:75]
	s_add_u32 s72, s72, 0x80
	s_addc_u32 s73, s73, 0
	s_add_u32 s74, s74, 0x80
	s_addc_u32 s75, s75, 0
	ds_read_b128 v[126:129], v217
	ds_read_b128 v[134:137], v221
	ds_read_b128 v[138:141], v221 offset:4096
	ds_read_b128 v[130:133], v217 offset:4096
	s_setprio 1
	s_waitcnt lgkmcnt(6)
	v_mfma_f32_32x32x16_bf16 v[50:65], v[108:111], v[116:119], v[50:65]
	s_waitcnt lgkmcnt(5)
	v_mfma_f32_32x32x16_bf16 v[18:33], v[108:111], v[120:123], v[18:33]
	s_waitcnt lgkmcnt(4)
	v_mfma_f32_32x32x16_bf16 v[34:49], v[112:115], v[116:119], v[34:49]
	v_mfma_f32_32x32x16_bf16 v[2:17], v[112:115], v[120:123], v[2:17]
	s_setprio 0
	ds_read_b128 v[108:111], v218
	ds_read_b128 v[116:119], v222
	ds_read_b128 v[120:123], v222 offset:4096
	ds_read_b128 v[112:115], v218 offset:4096
	s_setprio 1
	s_waitcnt lgkmcnt(6)
	v_mfma_f32_32x32x16_bf16 v[50:65], v[126:129], v[134:137], v[50:65]
	s_waitcnt lgkmcnt(5)
	v_mfma_f32_32x32x16_bf16 v[18:33], v[126:129], v[138:141], v[18:33]
	s_waitcnt lgkmcnt(4)
	v_mfma_f32_32x32x16_bf16 v[34:49], v[130:133], v[134:137], v[34:49]
	v_mfma_f32_32x32x16_bf16 v[2:17], v[130:133], v[138:141], v[2:17]
	s_setprio 0
	ds_read_b128 v[126:129], v219
	ds_read_b128 v[134:137], v223
	ds_read_b128 v[138:141], v223 offset:4096
	ds_read_b128 v[130:133], v219 offset:4096
	s_setprio 1
	s_waitcnt lgkmcnt(6)
	v_mfma_f32_32x32x16_bf16 v[50:65], v[108:111], v[116:119], v[50:65]
	s_waitcnt lgkmcnt(5)
	v_mfma_f32_32x32x16_bf16 v[18:33], v[108:111], v[120:123], v[18:33]
	s_waitcnt lgkmcnt(4)
	v_mfma_f32_32x32x16_bf16 v[34:49], v[112:115], v[116:119], v[34:49]
	v_mfma_f32_32x32x16_bf16 v[2:17], v[112:115], v[120:123], v[2:17]
	s_setprio 0
	s_waitcnt lgkmcnt(0)
	s_waitcnt vmcnt(6)
	s_barrier
	ds_read_b128 v[108:111], v216 offset:49152
	ds_read_b128 v[116:119], v220 offset:49152
	ds_read_b128 v[120:123], v220 offset:53248
	ds_read_b128 v[112:115], v216 offset:53248
	s_setprio 1
	v_mfma_f32_32x32x16_bf16 v[50:65], v[126:129], v[134:137], v[50:65]
	v_mfma_f32_32x32x16_bf16 v[18:33], v[126:129], v[138:141], v[18:33]
	v_mfma_f32_32x32x16_bf16 v[34:49], v[130:133], v[134:137], v[34:49]
	v_mfma_f32_32x32x16_bf16 v[2:17], v[130:133], v[138:141], v[2:17]
	s_setprio 0
	s_add_i32 m0, s79, 0x100
	s_nop 0
	global_load_lds_dwordx4 v144, s[72:73]
	s_add_i32 m0, s79, 0x2100
	s_nop 0
	global_load_lds_dwordx4 v145, s[72:73]
	s_add_i32 m0, s79, 0x4100
	s_nop 0
	global_load_lds_dwordx4 v144, s[74:75]
	s_add_i32 m0, s79, 0x6100
	s_nop 0
	global_load_lds_dwordx4 v145, s[74:75]
	s_add_i32 m0, s79, 0x8100
	s_nop 0
	global_load_lds_dwordx4 v146, s[74:75]
	s_add_i32 m0, s79, 0xa100
	s_nop 0
	global_load_lds_dwordx4 v147, s[74:75]
	s_add_u32 s72, s72, 0x80
	s_addc_u32 s73, s73, 0
	s_add_u32 s74, s74, 0x80
	s_addc_u32 s75, s75, 0
	ds_read_b128 v[126:129], v217 offset:49152
	ds_read_b128 v[134:137], v221 offset:49152
	ds_read_b128 v[138:141], v221 offset:53248
	ds_read_b128 v[130:133], v217 offset:53248
	s_setprio 1
	s_waitcnt lgkmcnt(6)
	v_mfma_f32_32x32x16_bf16 v[50:65], v[108:111], v[116:119], v[50:65]
	s_waitcnt lgkmcnt(5)
	v_mfma_f32_32x32x16_bf16 v[18:33], v[108:111], v[120:123], v[18:33]
	s_waitcnt lgkmcnt(4)
	v_mfma_f32_32x32x16_bf16 v[34:49], v[112:115], v[116:119], v[34:49]
	v_mfma_f32_32x32x16_bf16 v[2:17], v[112:115], v[120:123], v[2:17]
	s_setprio 0
	ds_read_b128 v[108:111], v218 offset:49152
	ds_read_b128 v[116:119], v222 offset:49152
	ds_read_b128 v[120:123], v222 offset:53248
	ds_read_b128 v[112:115], v218 offset:53248
	s_setprio 1
	s_waitcnt lgkmcnt(6)
	v_mfma_f32_32x32x16_bf16 v[50:65], v[126:129], v[134:137], v[50:65]
	s_waitcnt lgkmcnt(5)
	v_mfma_f32_32x32x16_bf16 v[18:33], v[126:129], v[138:141], v[18:33]
	s_waitcnt lgkmcnt(4)
	v_mfma_f32_32x32x16_bf16 v[34:49], v[130:133], v[134:137], v[34:49]
	v_mfma_f32_32x32x16_bf16 v[2:17], v[130:133], v[138:141], v[2:17]
	s_setprio 0
	ds_read_b128 v[126:129], v219 offset:49152
	ds_read_b128 v[134:137], v223 offset:49152
	ds_read_b128 v[138:141], v223 offset:53248
	ds_read_b128 v[130:133], v219 offset:53248
	s_setprio 1
	s_waitcnt lgkmcnt(6)
	v_mfma_f32_32x32x16_bf16 v[50:65], v[108:111], v[116:119], v[50:65]
	s_waitcnt lgkmcnt(5)
	v_mfma_f32_32x32x16_bf16 v[18:33], v[108:111], v[120:123], v[18:33]
	s_waitcnt lgkmcnt(4)
	v_mfma_f32_32x32x16_bf16 v[34:49], v[112:115], v[116:119], v[34:49]
	v_mfma_f32_32x32x16_bf16 v[2:17], v[112:115], v[120:123], v[2:17]
	s_setprio 0
	s_waitcnt lgkmcnt(0)
	s_waitcnt vmcnt(6)
	s_barrier
	ds_read_b128 v[108:111], v224
	ds_read_b128 v[116:119], v228
	ds_read_b128 v[120:123], v228 offset:4096
	ds_read_b128 v[112:115], v224 offset:4096
	s_setprio 1
	v_mfma_f32_32x32x16_bf16 v[50:65], v[126:129], v[134:137], v[50:65]
	v_mfma_f32_32x32x16_bf16 v[18:33], v[126:129], v[138:141], v[18:33]
	v_mfma_f32_32x32x16_bf16 v[34:49], v[130:133], v[134:137], v[34:49]
	v_mfma_f32_32x32x16_bf16 v[2:17], v[130:133], v[138:141], v[2:17]
	s_setprio 0
	s_add_i32 m0, s79, 0xc100
	s_nop 0
	global_load_lds_dwordx4 v144, s[72:73]
	s_add_i32 m0, s79, 0xe100
	s_nop 0
	global_load_lds_dwordx4 v145, s[72:73]
	s_add_i32 m0, s79, 0x10100
	s_nop 0
	global_load_lds_dwordx4 v144, s[74:75]
	s_add_i32 m0, s79, 0x12100
	s_nop 0
	global_load_lds_dwordx4 v145, s[74:75]
	s_add_i32 m0, s79, 0x14100
	s_nop 0
	global_load_lds_dwordx4 v146, s[74:75]
	s_add_i32 m0, s79, 0x16100
	s_nop 0
	global_load_lds_dwordx4 v147, s[74:75]
	s_add_u32 s72, s72, 0x80
	s_addc_u32 s73, s73, 0
	s_add_u32 s74, s74, 0x80
	s_addc_u32 s75, s75, 0
	ds_read_b128 v[126:129], v225
	ds_read_b128 v[134:137], v229
	ds_read_b128 v[138:141], v229 offset:4096
	ds_read_b128 v[130:133], v225 offset:4096
	s_setprio 1
	s_waitcnt lgkmcnt(6)
	v_mfma_f32_32x32x16_bf16 v[50:65], v[108:111], v[116:119], v[50:65]
	s_waitcnt lgkmcnt(5)
	v_mfma_f32_32x32x16_bf16 v[18:33], v[108:111], v[120:123], v[18:33]
	s_waitcnt lgkmcnt(4)
	v_mfma_f32_32x32x16_bf16 v[34:49], v[112:115], v[116:119], v[34:49]
	v_mfma_f32_32x32x16_bf16 v[2:17], v[112:115], v[120:123], v[2:17]
	s_setprio 0
	ds_read_b128 v[108:111], v226
	ds_read_b128 v[116:119], v230
	ds_read_b128 v[120:123], v230 offset:4096
	ds_read_b128 v[112:115], v226 offset:4096
	s_setprio 1
	s_waitcnt lgkmcnt(6)
	v_mfma_f32_32x32x16_bf16 v[50:65], v[126:129], v[134:137], v[50:65]
	s_waitcnt lgkmcnt(5)
	v_mfma_f32_32x32x16_bf16 v[18:33], v[126:129], v[138:141], v[18:33]
	s_waitcnt lgkmcnt(4)
	v_mfma_f32_32x32x16_bf16 v[34:49], v[130:133], v[134:137], v[34:49]
	v_mfma_f32_32x32x16_bf16 v[2:17], v[130:133], v[138:141], v[2:17]
	s_setprio 0
	ds_read_b128 v[126:129], v227
	ds_read_b128 v[134:137], v231
	ds_read_b128 v[138:141], v231 offset:4096
	ds_read_b128 v[130:133], v227 offset:4096
	s_setprio 1
	s_waitcnt lgkmcnt(6)
	v_mfma_f32_32x32x16_bf16 v[50:65], v[108:111], v[116:119], v[50:65]
	s_waitcnt lgkmcnt(5)
	v_mfma_f32_32x32x16_bf16 v[18:33], v[108:111], v[120:123], v[18:33]
	s_waitcnt lgkmcnt(4)
	v_mfma_f32_32x32x16_bf16 v[34:49], v[112:115], v[116:119], v[34:49]
	v_mfma_f32_32x32x16_bf16 v[2:17], v[112:115], v[120:123], v[2:17]
	s_setprio 0
	s_waitcnt lgkmcnt(0)
	s_waitcnt vmcnt(6)
	s_barrier
	ds_read_b128 v[108:111], v216
	ds_read_b128 v[116:119], v220
	ds_read_b128 v[120:123], v220 offset:4096
	ds_read_b128 v[112:115], v216 offset:4096
	s_setprio 1
	v_mfma_f32_32x32x16_bf16 v[50:65], v[126:129], v[134:137], v[50:65]
	v_mfma_f32_32x32x16_bf16 v[18:33], v[126:129], v[138:141], v[18:33]
	v_mfma_f32_32x32x16_bf16 v[34:49], v[130:133], v[134:137], v[34:49]
	v_mfma_f32_32x32x16_bf16 v[2:17], v[130:133], v[138:141], v[2:17]
	s_setprio 0
	s_add_i32 m0, s79, 0x1b900
	s_nop 0
	global_load_lds_dwordx4 v144, s[72:73]
	s_add_i32 m0, s79, 0x1d900
	s_nop 0
	global_load_lds_dwordx4 v145, s[72:73]
	s_add_i32 m0, s79, 0x1f900
	s_nop 0
	global_load_lds_dwordx4 v144, s[74:75]
	s_add_i32 m0, s79, 0x21900
	s_nop 0
	global_load_lds_dwordx4 v145, s[74:75]
	s_add_i32 m0, s79, 0x23900
	s_nop 0
	global_load_lds_dwordx4 v146, s[74:75]
	s_add_i32 m0, s79, 0x25900
	s_nop 0
	global_load_lds_dwordx4 v147, s[74:75]
	s_add_u32 s72, s72, 0x80
	s_addc_u32 s73, s73, 0
	s_add_u32 s74, s74, 0x80
	s_addc_u32 s75, s75, 0
	ds_read_b128 v[126:129], v217
	ds_read_b128 v[134:137], v221
	ds_read_b128 v[138:141], v221 offset:4096
	ds_read_b128 v[130:133], v217 offset:4096
	s_setprio 1
	s_waitcnt lgkmcnt(6)
	v_mfma_f32_32x32x16_bf16 v[50:65], v[108:111], v[116:119], v[50:65]
	s_waitcnt lgkmcnt(5)
	v_mfma_f32_32x32x16_bf16 v[18:33], v[108:111], v[120:123], v[18:33]
	s_waitcnt lgkmcnt(4)
	v_mfma_f32_32x32x16_bf16 v[34:49], v[112:115], v[116:119], v[34:49]
	v_mfma_f32_32x32x16_bf16 v[2:17], v[112:115], v[120:123], v[2:17]
	s_setprio 0
	ds_read_b128 v[108:111], v218
	ds_read_b128 v[116:119], v222
	ds_read_b128 v[120:123], v222 offset:4096
	ds_read_b128 v[112:115], v218 offset:4096
	s_setprio 1
	s_waitcnt lgkmcnt(6)
	v_mfma_f32_32x32x16_bf16 v[50:65], v[126:129], v[134:137], v[50:65]
	s_waitcnt lgkmcnt(5)
	v_mfma_f32_32x32x16_bf16 v[18:33], v[126:129], v[138:141], v[18:33]
	s_waitcnt lgkmcnt(4)
	v_mfma_f32_32x32x16_bf16 v[34:49], v[130:133], v[134:137], v[34:49]
	v_mfma_f32_32x32x16_bf16 v[2:17], v[130:133], v[138:141], v[2:17]
	s_setprio 0
	ds_read_b128 v[126:129], v219
	ds_read_b128 v[134:137], v223
	ds_read_b128 v[138:141], v223 offset:4096
	ds_read_b128 v[130:133], v219 offset:4096
	s_setprio 1
	s_waitcnt lgkmcnt(6)
	v_mfma_f32_32x32x16_bf16 v[50:65], v[108:111], v[116:119], v[50:65]
	s_waitcnt lgkmcnt(5)
	v_mfma_f32_32x32x16_bf16 v[18:33], v[108:111], v[120:123], v[18:33]
	s_waitcnt lgkmcnt(4)
	v_mfma_f32_32x32x16_bf16 v[34:49], v[112:115], v[116:119], v[34:49]
	v_mfma_f32_32x32x16_bf16 v[2:17], v[112:115], v[120:123], v[2:17]
	s_setprio 0
	s_waitcnt lgkmcnt(0)
	s_waitcnt vmcnt(6)
	s_barrier
	ds_read_b128 v[108:111], v216 offset:49152
	ds_read_b128 v[116:119], v220 offset:49152
	ds_read_b128 v[120:123], v220 offset:53248
	ds_read_b128 v[112:115], v216 offset:53248
	s_setprio 1
	v_mfma_f32_32x32x16_bf16 v[50:65], v[126:129], v[134:137], v[50:65]
	v_mfma_f32_32x32x16_bf16 v[18:33], v[126:129], v[138:141], v[18:33]
	v_mfma_f32_32x32x16_bf16 v[34:49], v[130:133], v[134:137], v[34:49]
	v_mfma_f32_32x32x16_bf16 v[2:17], v[130:133], v[138:141], v[2:17]
	s_setprio 0
	s_add_i32 m0, s79, 0x100
	s_nop 0
	global_load_lds_dwordx4 v144, s[72:73]
	s_add_i32 m0, s79, 0x2100
	s_nop 0
	global_load_lds_dwordx4 v145, s[72:73]
	s_add_i32 m0, s79, 0x4100
	s_nop 0
	global_load_lds_dwordx4 v144, s[74:75]
	s_add_i32 m0, s79, 0x6100
	s_nop 0
	global_load_lds_dwordx4 v145, s[74:75]
	s_add_i32 m0, s79, 0x8100
	s_nop 0
	global_load_lds_dwordx4 v146, s[74:75]
	s_add_i32 m0, s79, 0xa100
	s_nop 0
	global_load_lds_dwordx4 v147, s[74:75]
	s_add_u32 s72, s72, 0x80
	s_addc_u32 s73, s73, 0
	s_add_u32 s74, s74, 0x80
	s_addc_u32 s75, s75, 0
	ds_read_b128 v[126:129], v217 offset:49152
	ds_read_b128 v[134:137], v221 offset:49152
	ds_read_b128 v[138:141], v221 offset:53248
	ds_read_b128 v[130:133], v217 offset:53248
	s_setprio 1
	s_waitcnt lgkmcnt(6)
	v_mfma_f32_32x32x16_bf16 v[50:65], v[108:111], v[116:119], v[50:65]
	s_waitcnt lgkmcnt(5)
	v_mfma_f32_32x32x16_bf16 v[18:33], v[108:111], v[120:123], v[18:33]
	s_waitcnt lgkmcnt(4)
	v_mfma_f32_32x32x16_bf16 v[34:49], v[112:115], v[116:119], v[34:49]
	v_mfma_f32_32x32x16_bf16 v[2:17], v[112:115], v[120:123], v[2:17]
	s_setprio 0
	ds_read_b128 v[108:111], v218 offset:49152
	ds_read_b128 v[116:119], v222 offset:49152
	ds_read_b128 v[120:123], v222 offset:53248
	ds_read_b128 v[112:115], v218 offset:53248
	s_setprio 1
	s_waitcnt lgkmcnt(6)
	v_mfma_f32_32x32x16_bf16 v[50:65], v[126:129], v[134:137], v[50:65]
	s_waitcnt lgkmcnt(5)
	v_mfma_f32_32x32x16_bf16 v[18:33], v[126:129], v[138:141], v[18:33]
	s_waitcnt lgkmcnt(4)
	v_mfma_f32_32x32x16_bf16 v[34:49], v[130:133], v[134:137], v[34:49]
	v_mfma_f32_32x32x16_bf16 v[2:17], v[130:133], v[138:141], v[2:17]
	s_setprio 0
	ds_read_b128 v[126:129], v219 offset:49152
	ds_read_b128 v[134:137], v223 offset:49152
	ds_read_b128 v[138:141], v223 offset:53248
	ds_read_b128 v[130:133], v219 offset:53248
	s_setprio 1
	s_waitcnt lgkmcnt(6)
	v_mfma_f32_32x32x16_bf16 v[50:65], v[108:111], v[116:119], v[50:65]
	s_waitcnt lgkmcnt(5)
	v_mfma_f32_32x32x16_bf16 v[18:33], v[108:111], v[120:123], v[18:33]
	s_waitcnt lgkmcnt(4)
	v_mfma_f32_32x32x16_bf16 v[34:49], v[112:115], v[116:119], v[34:49]
	v_mfma_f32_32x32x16_bf16 v[2:17], v[112:115], v[120:123], v[2:17]
	s_setprio 0
	s_waitcnt lgkmcnt(0)
	s_waitcnt vmcnt(6)
	s_barrier
	ds_read_b128 v[108:111], v224
	ds_read_b128 v[116:119], v228
	ds_read_b128 v[120:123], v228 offset:4096
	ds_read_b128 v[112:115], v224 offset:4096
	s_setprio 1
	v_mfma_f32_32x32x16_bf16 v[50:65], v[126:129], v[134:137], v[50:65]
	v_mfma_f32_32x32x16_bf16 v[18:33], v[126:129], v[138:141], v[18:33]
	v_mfma_f32_32x32x16_bf16 v[34:49], v[130:133], v[134:137], v[34:49]
	v_mfma_f32_32x32x16_bf16 v[2:17], v[130:133], v[138:141], v[2:17]
	s_setprio 0
	s_add_i32 m0, s79, 0xc100
	s_nop 0
	global_load_lds_dwordx4 v144, s[72:73]
	s_add_i32 m0, s79, 0xe100
	s_nop 0
	global_load_lds_dwordx4 v145, s[72:73]
	s_add_i32 m0, s79, 0x10100
	s_nop 0
	global_load_lds_dwordx4 v144, s[74:75]
	s_add_i32 m0, s79, 0x12100
	s_nop 0
	global_load_lds_dwordx4 v145, s[74:75]
	s_add_i32 m0, s79, 0x14100
	s_nop 0
	global_load_lds_dwordx4 v146, s[74:75]
	s_add_i32 m0, s79, 0x16100
	s_nop 0
	global_load_lds_dwordx4 v147, s[74:75]
	s_add_u32 s72, s72, 0x80
	s_addc_u32 s73, s73, 0
	s_add_u32 s74, s74, 0x80
	s_addc_u32 s75, s75, 0
	ds_read_b128 v[126:129], v225
	ds_read_b128 v[134:137], v229
	ds_read_b128 v[138:141], v229 offset:4096
	ds_read_b128 v[130:133], v225 offset:4096
	s_setprio 1
	s_waitcnt lgkmcnt(6)
	v_mfma_f32_32x32x16_bf16 v[50:65], v[108:111], v[116:119], v[50:65]
	s_waitcnt lgkmcnt(5)
	v_mfma_f32_32x32x16_bf16 v[18:33], v[108:111], v[120:123], v[18:33]
	s_waitcnt lgkmcnt(4)
	v_mfma_f32_32x32x16_bf16 v[34:49], v[112:115], v[116:119], v[34:49]
	v_mfma_f32_32x32x16_bf16 v[2:17], v[112:115], v[120:123], v[2:17]
	s_setprio 0
	ds_read_b128 v[108:111], v226
	ds_read_b128 v[116:119], v230
	ds_read_b128 v[120:123], v230 offset:4096
	ds_read_b128 v[112:115], v226 offset:4096
	s_setprio 1
	s_waitcnt lgkmcnt(6)
	v_mfma_f32_32x32x16_bf16 v[50:65], v[126:129], v[134:137], v[50:65]
	s_waitcnt lgkmcnt(5)
	v_mfma_f32_32x32x16_bf16 v[18:33], v[126:129], v[138:141], v[18:33]
	s_waitcnt lgkmcnt(4)
	v_mfma_f32_32x32x16_bf16 v[34:49], v[130:133], v[134:137], v[34:49]
	v_mfma_f32_32x32x16_bf16 v[2:17], v[130:133], v[138:141], v[2:17]
	s_setprio 0
	ds_read_b128 v[126:129], v227
	ds_read_b128 v[134:137], v231
	ds_read_b128 v[138:141], v231 offset:4096
	ds_read_b128 v[130:133], v227 offset:4096
	s_setprio 1
	s_waitcnt lgkmcnt(6)
	v_mfma_f32_32x32x16_bf16 v[50:65], v[108:111], v[116:119], v[50:65]
	s_waitcnt lgkmcnt(5)
	v_mfma_f32_32x32x16_bf16 v[18:33], v[108:111], v[120:123], v[18:33]
	s_waitcnt lgkmcnt(4)
	v_mfma_f32_32x32x16_bf16 v[34:49], v[112:115], v[116:119], v[34:49]
	v_mfma_f32_32x32x16_bf16 v[2:17], v[112:115], v[120:123], v[2:17]
	s_setprio 0
	s_waitcnt lgkmcnt(0)
	s_waitcnt vmcnt(6)
	s_barrier
	ds_read_b128 v[108:111], v216
	ds_read_b128 v[116:119], v220
	ds_read_b128 v[120:123], v220 offset:4096
	ds_read_b128 v[112:115], v216 offset:4096
	s_setprio 1
	v_mfma_f32_32x32x16_bf16 v[50:65], v[126:129], v[134:137], v[50:65]
	v_mfma_f32_32x32x16_bf16 v[18:33], v[126:129], v[138:141], v[18:33]
	v_mfma_f32_32x32x16_bf16 v[34:49], v[130:133], v[134:137], v[34:49]
	v_mfma_f32_32x32x16_bf16 v[2:17], v[130:133], v[138:141], v[2:17]
	s_setprio 0
	s_add_i32 m0, s79, 0x1b900
	s_nop 0
	global_load_lds_dwordx4 v144, s[72:73]
	s_add_i32 m0, s79, 0x1d900
	s_nop 0
	global_load_lds_dwordx4 v145, s[72:73]
	s_add_i32 m0, s79, 0x1f900
	s_nop 0
	global_load_lds_dwordx4 v144, s[74:75]
	s_add_i32 m0, s79, 0x21900
	s_nop 0
	global_load_lds_dwordx4 v145, s[74:75]
	s_add_i32 m0, s79, 0x23900
	s_nop 0
	global_load_lds_dwordx4 v146, s[74:75]
	s_add_i32 m0, s79, 0x25900
	s_nop 0
	global_load_lds_dwordx4 v147, s[74:75]
	s_add_u32 s72, s72, 0x80
	s_addc_u32 s73, s73, 0
	s_add_u32 s74, s74, 0x80
	s_addc_u32 s75, s75, 0
	ds_read_b128 v[126:129], v217
	ds_read_b128 v[134:137], v221
	ds_read_b128 v[138:141], v221 offset:4096
	ds_read_b128 v[130:133], v217 offset:4096
	s_setprio 1
	s_waitcnt lgkmcnt(6)
	v_mfma_f32_32x32x16_bf16 v[50:65], v[108:111], v[116:119], v[50:65]
	s_waitcnt lgkmcnt(5)
	v_mfma_f32_32x32x16_bf16 v[18:33], v[108:111], v[120:123], v[18:33]
	s_waitcnt lgkmcnt(4)
	v_mfma_f32_32x32x16_bf16 v[34:49], v[112:115], v[116:119], v[34:49]
	v_mfma_f32_32x32x16_bf16 v[2:17], v[112:115], v[120:123], v[2:17]
	s_setprio 0
	ds_read_b128 v[108:111], v218
	ds_read_b128 v[116:119], v222
	ds_read_b128 v[120:123], v222 offset:4096
	ds_read_b128 v[112:115], v218 offset:4096
	s_setprio 1
	s_waitcnt lgkmcnt(6)
	v_mfma_f32_32x32x16_bf16 v[50:65], v[126:129], v[134:137], v[50:65]
	s_waitcnt lgkmcnt(5)
	v_mfma_f32_32x32x16_bf16 v[18:33], v[126:129], v[138:141], v[18:33]
	s_waitcnt lgkmcnt(4)
	v_mfma_f32_32x32x16_bf16 v[34:49], v[130:133], v[134:137], v[34:49]
	v_mfma_f32_32x32x16_bf16 v[2:17], v[130:133], v[138:141], v[2:17]
	s_setprio 0
	ds_read_b128 v[126:129], v219
	ds_read_b128 v[134:137], v223
	ds_read_b128 v[138:141], v223 offset:4096
	ds_read_b128 v[130:133], v219 offset:4096
	s_setprio 1
	s_waitcnt lgkmcnt(6)
	v_mfma_f32_32x32x16_bf16 v[50:65], v[108:111], v[116:119], v[50:65]
	s_waitcnt lgkmcnt(5)
	v_mfma_f32_32x32x16_bf16 v[18:33], v[108:111], v[120:123], v[18:33]
	s_waitcnt lgkmcnt(4)
	v_mfma_f32_32x32x16_bf16 v[34:49], v[112:115], v[116:119], v[34:49]
	v_mfma_f32_32x32x16_bf16 v[2:17], v[112:115], v[120:123], v[2:17]
	s_setprio 0
	s_waitcnt lgkmcnt(0)
	s_waitcnt vmcnt(6)
	s_barrier
	ds_read_b128 v[108:111], v216 offset:49152
	ds_read_b128 v[116:119], v220 offset:49152
	ds_read_b128 v[120:123], v220 offset:53248
	ds_read_b128 v[112:115], v216 offset:53248
	s_setprio 1
	v_mfma_f32_32x32x16_bf16 v[50:65], v[126:129], v[134:137], v[50:65]
	v_mfma_f32_32x32x16_bf16 v[18:33], v[126:129], v[138:141], v[18:33]
	v_mfma_f32_32x32x16_bf16 v[34:49], v[130:133], v[134:137], v[34:49]
	v_mfma_f32_32x32x16_bf16 v[2:17], v[130:133], v[138:141], v[2:17]
	s_setprio 0
	s_add_i32 m0, s79, 0x100
	s_nop 0
	global_load_lds_dwordx4 v144, s[72:73]
	s_add_i32 m0, s79, 0x2100
	s_nop 0
	global_load_lds_dwordx4 v145, s[72:73]
	s_add_i32 m0, s79, 0x4100
	s_nop 0
	global_load_lds_dwordx4 v144, s[74:75]
	s_add_i32 m0, s79, 0x6100
	s_nop 0
	global_load_lds_dwordx4 v145, s[74:75]
	s_add_i32 m0, s79, 0x8100
	s_nop 0
	global_load_lds_dwordx4 v146, s[74:75]
	s_add_i32 m0, s79, 0xa100
	s_nop 0
	global_load_lds_dwordx4 v147, s[74:75]
	s_add_u32 s72, s72, 0x80
	s_addc_u32 s73, s73, 0
	s_add_u32 s74, s74, 0x80
	s_addc_u32 s75, s75, 0
	ds_read_b128 v[126:129], v217 offset:49152
	ds_read_b128 v[134:137], v221 offset:49152
	ds_read_b128 v[138:141], v221 offset:53248
	ds_read_b128 v[130:133], v217 offset:53248
	s_setprio 1
	s_waitcnt lgkmcnt(6)
	v_mfma_f32_32x32x16_bf16 v[50:65], v[108:111], v[116:119], v[50:65]
	s_waitcnt lgkmcnt(5)
	v_mfma_f32_32x32x16_bf16 v[18:33], v[108:111], v[120:123], v[18:33]
	s_waitcnt lgkmcnt(4)
	v_mfma_f32_32x32x16_bf16 v[34:49], v[112:115], v[116:119], v[34:49]
	v_mfma_f32_32x32x16_bf16 v[2:17], v[112:115], v[120:123], v[2:17]
	s_setprio 0
	ds_read_b128 v[108:111], v218 offset:49152
	ds_read_b128 v[116:119], v222 offset:49152
	ds_read_b128 v[120:123], v222 offset:53248
	ds_read_b128 v[112:115], v218 offset:53248
	s_setprio 1
	s_waitcnt lgkmcnt(6)
	v_mfma_f32_32x32x16_bf16 v[50:65], v[126:129], v[134:137], v[50:65]
	s_waitcnt lgkmcnt(5)
	v_mfma_f32_32x32x16_bf16 v[18:33], v[126:129], v[138:141], v[18:33]
	s_waitcnt lgkmcnt(4)
	v_mfma_f32_32x32x16_bf16 v[34:49], v[130:133], v[134:137], v[34:49]
	v_mfma_f32_32x32x16_bf16 v[2:17], v[130:133], v[138:141], v[2:17]
	s_setprio 0
	ds_read_b128 v[126:129], v219 offset:49152
	ds_read_b128 v[134:137], v223 offset:49152
	ds_read_b128 v[138:141], v223 offset:53248
	ds_read_b128 v[130:133], v219 offset:53248
	s_setprio 1
	s_waitcnt lgkmcnt(6)
	v_mfma_f32_32x32x16_bf16 v[50:65], v[108:111], v[116:119], v[50:65]
	s_waitcnt lgkmcnt(5)
	v_mfma_f32_32x32x16_bf16 v[18:33], v[108:111], v[120:123], v[18:33]
	s_waitcnt lgkmcnt(4)
	v_mfma_f32_32x32x16_bf16 v[34:49], v[112:115], v[116:119], v[34:49]
	v_mfma_f32_32x32x16_bf16 v[2:17], v[112:115], v[120:123], v[2:17]
	s_setprio 0
	s_waitcnt lgkmcnt(0)
	s_waitcnt vmcnt(6)
	s_barrier
	ds_read_b128 v[108:111], v224
	ds_read_b128 v[116:119], v228
	ds_read_b128 v[120:123], v228 offset:4096
	ds_read_b128 v[112:115], v224 offset:4096
	s_setprio 1
	v_mfma_f32_32x32x16_bf16 v[50:65], v[126:129], v[134:137], v[50:65]
	v_mfma_f32_32x32x16_bf16 v[18:33], v[126:129], v[138:141], v[18:33]
	v_mfma_f32_32x32x16_bf16 v[34:49], v[130:133], v[134:137], v[34:49]
	v_mfma_f32_32x32x16_bf16 v[2:17], v[130:133], v[138:141], v[2:17]
	s_setprio 0
	s_add_i32 m0, s79, 0xc100
	s_nop 0
	global_load_lds_dwordx4 v144, s[72:73]
	s_add_i32 m0, s79, 0xe100
	s_nop 0
	global_load_lds_dwordx4 v145, s[72:73]
	s_add_i32 m0, s79, 0x10100
	s_nop 0
	global_load_lds_dwordx4 v144, s[74:75]
	s_add_i32 m0, s79, 0x12100
	s_nop 0
	global_load_lds_dwordx4 v145, s[74:75]
	s_add_i32 m0, s79, 0x14100
	s_nop 0
	global_load_lds_dwordx4 v146, s[74:75]
	s_add_i32 m0, s79, 0x16100
	s_nop 0
	global_load_lds_dwordx4 v147, s[74:75]
	s_add_u32 s72, s72, 0x80
	s_addc_u32 s73, s73, 0
	s_add_u32 s74, s74, 0x80
	s_addc_u32 s75, s75, 0
	ds_read_b128 v[126:129], v225
	ds_read_b128 v[134:137], v229
	ds_read_b128 v[138:141], v229 offset:4096
	ds_read_b128 v[130:133], v225 offset:4096
	s_setprio 1
	s_waitcnt lgkmcnt(6)
	v_mfma_f32_32x32x16_bf16 v[50:65], v[108:111], v[116:119], v[50:65]
	s_waitcnt lgkmcnt(5)
	v_mfma_f32_32x32x16_bf16 v[18:33], v[108:111], v[120:123], v[18:33]
	s_waitcnt lgkmcnt(4)
	v_mfma_f32_32x32x16_bf16 v[34:49], v[112:115], v[116:119], v[34:49]
	v_mfma_f32_32x32x16_bf16 v[2:17], v[112:115], v[120:123], v[2:17]
	s_setprio 0
	ds_read_b128 v[108:111], v226
	ds_read_b128 v[116:119], v230
	ds_read_b128 v[120:123], v230 offset:4096
	ds_read_b128 v[112:115], v226 offset:4096
	s_setprio 1
	s_waitcnt lgkmcnt(6)
	v_mfma_f32_32x32x16_bf16 v[50:65], v[126:129], v[134:137], v[50:65]
	s_waitcnt lgkmcnt(5)
	v_mfma_f32_32x32x16_bf16 v[18:33], v[126:129], v[138:141], v[18:33]
	s_waitcnt lgkmcnt(4)
	v_mfma_f32_32x32x16_bf16 v[34:49], v[130:133], v[134:137], v[34:49]
	v_mfma_f32_32x32x16_bf16 v[2:17], v[130:133], v[138:141], v[2:17]
	s_setprio 0
	ds_read_b128 v[126:129], v227
	ds_read_b128 v[134:137], v231
	ds_read_b128 v[138:141], v231 offset:4096
	ds_read_b128 v[130:133], v227 offset:4096
	s_setprio 1
	s_waitcnt lgkmcnt(6)
	v_mfma_f32_32x32x16_bf16 v[50:65], v[108:111], v[116:119], v[50:65]
	s_waitcnt lgkmcnt(5)
	v_mfma_f32_32x32x16_bf16 v[18:33], v[108:111], v[120:123], v[18:33]
	s_waitcnt lgkmcnt(4)
	v_mfma_f32_32x32x16_bf16 v[34:49], v[112:115], v[116:119], v[34:49]
	v_mfma_f32_32x32x16_bf16 v[2:17], v[112:115], v[120:123], v[2:17]
	s_setprio 0
	s_waitcnt lgkmcnt(0)
	s_waitcnt vmcnt(6)
	s_barrier
	ds_read_b128 v[108:111], v216
	ds_read_b128 v[116:119], v220
	ds_read_b128 v[120:123], v220 offset:4096
	ds_read_b128 v[112:115], v216 offset:4096
	s_setprio 1
	v_mfma_f32_32x32x16_bf16 v[50:65], v[126:129], v[134:137], v[50:65]
	v_mfma_f32_32x32x16_bf16 v[18:33], v[126:129], v[138:141], v[18:33]
	v_mfma_f32_32x32x16_bf16 v[34:49], v[130:133], v[134:137], v[34:49]
	v_mfma_f32_32x32x16_bf16 v[2:17], v[130:133], v[138:141], v[2:17]
	s_setprio 0
	s_add_i32 m0, s79, 0x1b900
	s_nop 0
	global_load_lds_dwordx4 v144, s[72:73]
	s_add_i32 m0, s79, 0x1d900
	s_nop 0
	global_load_lds_dwordx4 v145, s[72:73]
	s_add_i32 m0, s79, 0x1f900
	s_nop 0
	global_load_lds_dwordx4 v144, s[74:75]
	s_add_i32 m0, s79, 0x21900
	s_nop 0
	global_load_lds_dwordx4 v145, s[74:75]
	s_add_i32 m0, s79, 0x23900
	s_nop 0
	global_load_lds_dwordx4 v146, s[74:75]
	s_add_i32 m0, s79, 0x25900
	s_nop 0
	global_load_lds_dwordx4 v147, s[74:75]
	s_add_u32 s72, s72, 0x80
	s_addc_u32 s73, s73, 0
	s_add_u32 s74, s74, 0x80
	s_addc_u32 s75, s75, 0
	ds_read_b128 v[126:129], v217
	ds_read_b128 v[134:137], v221
	ds_read_b128 v[138:141], v221 offset:4096
	ds_read_b128 v[130:133], v217 offset:4096
	s_setprio 1
	s_waitcnt lgkmcnt(6)
	v_mfma_f32_32x32x16_bf16 v[50:65], v[108:111], v[116:119], v[50:65]
	s_waitcnt lgkmcnt(5)
	v_mfma_f32_32x32x16_bf16 v[18:33], v[108:111], v[120:123], v[18:33]
	s_waitcnt lgkmcnt(4)
	v_mfma_f32_32x32x16_bf16 v[34:49], v[112:115], v[116:119], v[34:49]
	v_mfma_f32_32x32x16_bf16 v[2:17], v[112:115], v[120:123], v[2:17]
	s_setprio 0
	ds_read_b128 v[108:111], v218
	ds_read_b128 v[116:119], v222
	ds_read_b128 v[120:123], v222 offset:4096
	ds_read_b128 v[112:115], v218 offset:4096
	s_setprio 1
	s_waitcnt lgkmcnt(6)
	v_mfma_f32_32x32x16_bf16 v[50:65], v[126:129], v[134:137], v[50:65]
	s_waitcnt lgkmcnt(5)
	v_mfma_f32_32x32x16_bf16 v[18:33], v[126:129], v[138:141], v[18:33]
	s_waitcnt lgkmcnt(4)
	v_mfma_f32_32x32x16_bf16 v[34:49], v[130:133], v[134:137], v[34:49]
	v_mfma_f32_32x32x16_bf16 v[2:17], v[130:133], v[138:141], v[2:17]
	s_setprio 0
	ds_read_b128 v[126:129], v219
	ds_read_b128 v[134:137], v223
	ds_read_b128 v[138:141], v223 offset:4096
	ds_read_b128 v[130:133], v219 offset:4096
	s_setprio 1
	s_waitcnt lgkmcnt(6)
	v_mfma_f32_32x32x16_bf16 v[50:65], v[108:111], v[116:119], v[50:65]
	s_waitcnt lgkmcnt(5)
	v_mfma_f32_32x32x16_bf16 v[18:33], v[108:111], v[120:123], v[18:33]
	s_waitcnt lgkmcnt(4)
	v_mfma_f32_32x32x16_bf16 v[34:49], v[112:115], v[116:119], v[34:49]
	v_mfma_f32_32x32x16_bf16 v[2:17], v[112:115], v[120:123], v[2:17]
	s_setprio 0
	s_waitcnt lgkmcnt(0)
	s_waitcnt vmcnt(6)
	s_barrier
	ds_read_b128 v[108:111], v216 offset:49152
	ds_read_b128 v[116:119], v220 offset:49152
	ds_read_b128 v[120:123], v220 offset:53248
	ds_read_b128 v[112:115], v216 offset:53248
	s_setprio 1
	v_mfma_f32_32x32x16_bf16 v[50:65], v[126:129], v[134:137], v[50:65]
	v_mfma_f32_32x32x16_bf16 v[18:33], v[126:129], v[138:141], v[18:33]
	v_mfma_f32_32x32x16_bf16 v[34:49], v[130:133], v[134:137], v[34:49]
	v_mfma_f32_32x32x16_bf16 v[2:17], v[130:133], v[138:141], v[2:17]
	s_setprio 0
	s_add_i32 m0, s79, 0x100
	s_nop 0
	global_load_lds_dwordx4 v144, s[72:73]
	s_add_i32 m0, s79, 0x2100
	s_nop 0
	global_load_lds_dwordx4 v145, s[72:73]
	s_add_i32 m0, s79, 0x4100
	s_nop 0
	global_load_lds_dwordx4 v144, s[74:75]
	s_add_i32 m0, s79, 0x6100
	s_nop 0
	global_load_lds_dwordx4 v145, s[74:75]
	s_add_i32 m0, s79, 0x8100
	s_nop 0
	global_load_lds_dwordx4 v146, s[74:75]
	s_add_i32 m0, s79, 0xa100
	s_nop 0
	global_load_lds_dwordx4 v147, s[74:75]
	s_add_u32 s72, s72, 0x80
	s_addc_u32 s73, s73, 0
	s_add_u32 s74, s74, 0x80
	s_addc_u32 s75, s75, 0
	ds_read_b128 v[126:129], v217 offset:49152
	ds_read_b128 v[134:137], v221 offset:49152
	ds_read_b128 v[138:141], v221 offset:53248
	ds_read_b128 v[130:133], v217 offset:53248
	s_setprio 1
	s_waitcnt lgkmcnt(6)
	v_mfma_f32_32x32x16_bf16 v[50:65], v[108:111], v[116:119], v[50:65]
	s_waitcnt lgkmcnt(5)
	v_mfma_f32_32x32x16_bf16 v[18:33], v[108:111], v[120:123], v[18:33]
	s_waitcnt lgkmcnt(4)
	v_mfma_f32_32x32x16_bf16 v[34:49], v[112:115], v[116:119], v[34:49]
	v_mfma_f32_32x32x16_bf16 v[2:17], v[112:115], v[120:123], v[2:17]
	s_setprio 0
	ds_read_b128 v[108:111], v218 offset:49152
	ds_read_b128 v[116:119], v222 offset:49152
	ds_read_b128 v[120:123], v222 offset:53248
	ds_read_b128 v[112:115], v218 offset:53248
	s_setprio 1
	s_waitcnt lgkmcnt(6)
	v_mfma_f32_32x32x16_bf16 v[50:65], v[126:129], v[134:137], v[50:65]
	s_waitcnt lgkmcnt(5)
	v_mfma_f32_32x32x16_bf16 v[18:33], v[126:129], v[138:141], v[18:33]
	s_waitcnt lgkmcnt(4)
	v_mfma_f32_32x32x16_bf16 v[34:49], v[130:133], v[134:137], v[34:49]
	v_mfma_f32_32x32x16_bf16 v[2:17], v[130:133], v[138:141], v[2:17]
	s_setprio 0
	ds_read_b128 v[126:129], v219 offset:49152
	ds_read_b128 v[134:137], v223 offset:49152
	ds_read_b128 v[138:141], v223 offset:53248
	ds_read_b128 v[130:133], v219 offset:53248
	s_setprio 1
	s_waitcnt lgkmcnt(6)
	v_mfma_f32_32x32x16_bf16 v[50:65], v[108:111], v[116:119], v[50:65]
	s_waitcnt lgkmcnt(5)
	v_mfma_f32_32x32x16_bf16 v[18:33], v[108:111], v[120:123], v[18:33]
	s_waitcnt lgkmcnt(4)
	v_mfma_f32_32x32x16_bf16 v[34:49], v[112:115], v[116:119], v[34:49]
	v_mfma_f32_32x32x16_bf16 v[2:17], v[112:115], v[120:123], v[2:17]
	s_setprio 0
	s_waitcnt lgkmcnt(0)
	s_waitcnt vmcnt(6)
	s_barrier
	ds_read_b128 v[108:111], v224
	ds_read_b128 v[116:119], v228
	ds_read_b128 v[120:123], v228 offset:4096
	ds_read_b128 v[112:115], v224 offset:4096
	s_setprio 1
	v_mfma_f32_32x32x16_bf16 v[50:65], v[126:129], v[134:137], v[50:65]
	v_mfma_f32_32x32x16_bf16 v[18:33], v[126:129], v[138:141], v[18:33]
	v_mfma_f32_32x32x16_bf16 v[34:49], v[130:133], v[134:137], v[34:49]
	v_mfma_f32_32x32x16_bf16 v[2:17], v[130:133], v[138:141], v[2:17]
	s_setprio 0
	ds_read_b128 v[126:129], v225
	ds_read_b128 v[134:137], v229
	ds_read_b128 v[138:141], v229 offset:4096
	ds_read_b128 v[130:133], v225 offset:4096
	s_setprio 1
	s_waitcnt lgkmcnt(6)
	v_mfma_f32_32x32x16_bf16 v[50:65], v[108:111], v[116:119], v[50:65]
	s_waitcnt lgkmcnt(5)
	v_mfma_f32_32x32x16_bf16 v[18:33], v[108:111], v[120:123], v[18:33]
	s_waitcnt lgkmcnt(4)
	v_mfma_f32_32x32x16_bf16 v[34:49], v[112:115], v[116:119], v[34:49]
	v_mfma_f32_32x32x16_bf16 v[2:17], v[112:115], v[120:123], v[2:17]
	s_setprio 0
	ds_read_b128 v[108:111], v226
	ds_read_b128 v[116:119], v230
	ds_read_b128 v[120:123], v230 offset:4096
	ds_read_b128 v[112:115], v226 offset:4096
	s_setprio 1
	s_waitcnt lgkmcnt(6)
	v_mfma_f32_32x32x16_bf16 v[50:65], v[126:129], v[134:137], v[50:65]
	s_waitcnt lgkmcnt(5)
	v_mfma_f32_32x32x16_bf16 v[18:33], v[126:129], v[138:141], v[18:33]
	s_waitcnt lgkmcnt(4)
	v_mfma_f32_32x32x16_bf16 v[34:49], v[130:133], v[134:137], v[34:49]
	v_mfma_f32_32x32x16_bf16 v[2:17], v[130:133], v[138:141], v[2:17]
	s_setprio 0
	ds_read_b128 v[126:129], v227
	ds_read_b128 v[134:137], v231
	ds_read_b128 v[138:141], v231 offset:4096
	ds_read_b128 v[130:133], v227 offset:4096
	s_setprio 1
	s_waitcnt lgkmcnt(6)
	v_mfma_f32_32x32x16_bf16 v[50:65], v[108:111], v[116:119], v[50:65]
	s_waitcnt lgkmcnt(5)
	v_mfma_f32_32x32x16_bf16 v[18:33], v[108:111], v[120:123], v[18:33]
	s_waitcnt lgkmcnt(4)
	v_mfma_f32_32x32x16_bf16 v[34:49], v[112:115], v[116:119], v[34:49]
	v_mfma_f32_32x32x16_bf16 v[2:17], v[112:115], v[120:123], v[2:17]
	s_setprio 0
	s_waitcnt lgkmcnt(0)
	s_waitcnt vmcnt(0)
	s_barrier
	ds_read_b128 v[108:111], v216
	ds_read_b128 v[116:119], v220
	ds_read_b128 v[120:123], v220 offset:4096
	ds_read_b128 v[112:115], v216 offset:4096
	s_setprio 1
	v_mfma_f32_32x32x16_bf16 v[50:65], v[126:129], v[134:137], v[50:65]
	v_mfma_f32_32x32x16_bf16 v[18:33], v[126:129], v[138:141], v[18:33]
	v_mfma_f32_32x32x16_bf16 v[34:49], v[130:133], v[134:137], v[34:49]
	v_mfma_f32_32x32x16_bf16 v[2:17], v[130:133], v[138:141], v[2:17]
	s_setprio 0
	ds_read_b128 v[126:129], v217
	ds_read_b128 v[134:137], v221
	ds_read_b128 v[138:141], v221 offset:4096
	ds_read_b128 v[130:133], v217 offset:4096
	s_setprio 1
	s_waitcnt lgkmcnt(6)
	v_mfma_f32_32x32x16_bf16 v[50:65], v[108:111], v[116:119], v[50:65]
	s_waitcnt lgkmcnt(5)
	v_mfma_f32_32x32x16_bf16 v[18:33], v[108:111], v[120:123], v[18:33]
	s_waitcnt lgkmcnt(4)
	v_mfma_f32_32x32x16_bf16 v[34:49], v[112:115], v[116:119], v[34:49]
	v_mfma_f32_32x32x16_bf16 v[2:17], v[112:115], v[120:123], v[2:17]
	s_setprio 0
	ds_read_b128 v[108:111], v218
	ds_read_b128 v[116:119], v222
	ds_read_b128 v[120:123], v222 offset:4096
	ds_read_b128 v[112:115], v218 offset:4096
	s_setprio 1
	s_waitcnt lgkmcnt(6)
	v_mfma_f32_32x32x16_bf16 v[50:65], v[126:129], v[134:137], v[50:65]
	s_waitcnt lgkmcnt(5)
	v_mfma_f32_32x32x16_bf16 v[18:33], v[126:129], v[138:141], v[18:33]
	s_waitcnt lgkmcnt(4)
	v_mfma_f32_32x32x16_bf16 v[34:49], v[130:133], v[134:137], v[34:49]
	v_mfma_f32_32x32x16_bf16 v[2:17], v[130:133], v[138:141], v[2:17]
	s_setprio 0
	ds_read_b128 v[126:129], v219
	ds_read_b128 v[134:137], v223
	ds_read_b128 v[138:141], v223 offset:4096
	ds_read_b128 v[130:133], v219 offset:4096
	s_setprio 1
	s_waitcnt lgkmcnt(6)
	v_mfma_f32_32x32x16_bf16 v[50:65], v[108:111], v[116:119], v[50:65]
	s_waitcnt lgkmcnt(5)
	v_mfma_f32_32x32x16_bf16 v[18:33], v[108:111], v[120:123], v[18:33]
	s_waitcnt lgkmcnt(4)
	v_mfma_f32_32x32x16_bf16 v[34:49], v[112:115], v[116:119], v[34:49]
	v_mfma_f32_32x32x16_bf16 v[2:17], v[112:115], v[120:123], v[2:17]
	s_setprio 0
	s_waitcnt lgkmcnt(0)
	s_waitcnt vmcnt(0)
	s_barrier

.Lg2_ptr:
	s_load_dwordx2 s[30:31], s[34:35], 0x0
	v_readfirstlane_b32 s34, v184
	s_nop 3
	s_lshr_b32 s6, s34, 4
	s_and_b32 s6, s6, 4
	v_bitop3_b32 v6, s6, v208, v209 bitop3:0x36
	v_lshl_or_b32 v2, s49, 3, v210
	v_lshlrev_b32_e32 v2, 11, v2
	v_lshlrev_b32_e32 v6, 4, v6
	v_or_b32_e32 v124, v2, v6
	v_add_u32_e32 v125, 0x20000, v124
	v_add_u32_e32 v126, 0x40000, v124
	v_add_u32_e32 v127, 0x60000, v124
	s_lshl_b32 s19, s49, 10
	s_and_b32 s6, s34, 64
	v_or_b32_e32 v2, s6, v189
	v_lshlrev_b32_e32 v118, 7, v2
	s_lshr_b32 s6, s34, 1
	s_and_b32 s50, s6, 0x7fffffc0
	v_or_b32_e32 v2, s50, v189
	v_lshlrev_b32_e32 v119, 7, v2
	s_mulk_i32 s49, 0x3000
	s_add_i32 s34, s49, 0x100
	v_add3_u32 v240, s34, v72, v74
	v_add3_u32 v83, s34, v187, v73
	s_add_i32 s4, s50, s48
	v_add_u32_e32 v216, s4, v75
	v_add_u32_e32 v217, s4, v76
	v_add_u32_e32 v218, s4, v77
	v_add_u32_e32 v219, s4, v78
	v_add_u32_e32 v220, s4, v79
	v_add_u32_e32 v221, s4, v80
	v_add_u32_e32 v222, s4, v81
	v_add_u32_e32 v223, s4, v82
	v_lshlrev_b32_e32 v216, 2, v216
	v_lshlrev_b32_e32 v217, 2, v217
	v_lshlrev_b32_e32 v218, 2, v218
	v_lshlrev_b32_e32 v219, 2, v219
	v_lshlrev_b32_e32 v220, 2, v220
	v_lshlrev_b32_e32 v221, 2, v221
	v_lshlrev_b32_e32 v222, 2, v222
	v_lshlrev_b32_e32 v223, 2, v223
	v_lshlrev_b32_e32 v68, 2, v188
	s_lshl_b64 s[28:29], s[28:29], 2
	s_add_u32 s6, s54, s28
	s_addc_u32 s7, s55, s29
	s_lshl_b64 s[28:29], s[4:5], 2
	s_add_u32 s28, s6, s28
	s_addc_u32 s29, s7, s29
	v_lshl_add_u64 v[64:65], s[28:29], 0, v[68:69]
	v_add_co_u32_e32 v64, vcc, s46, v64
	s_nop 1
	v_addc_co_u32_e32 v65, vcc, 0, v65, vcc
	s_waitcnt lgkmcnt(0)
	s_add_u32 s26, s30, s26
	s_addc_u32 s27, s31, s27
	s_add_u32 s8, s26, 0x20000
	s_addc_u32 s9, s27, 0
	s_add_u32 s10, s24, 0x20000
	s_addc_u32 s11, s25, 0
	s_add_i32 m0, s19, 0x100
	s_nop 0
	global_load_lds_dwordx4 v124, s[12:13]
	s_add_i32 m0, s19, 0x2100
	s_nop 0
	global_load_lds_dwordx4 v125, s[12:13]
	s_add_i32 m0, s19, 0x4100
	s_nop 0
	global_load_lds_dwordx4 v124, s[14:15]
	s_add_i32 m0, s19, 0x6100
	s_nop 0
	global_load_lds_dwordx4 v125, s[14:15]
	s_add_i32 m0, s19, 0x8100
	s_nop 0
	global_load_lds_dwordx4 v126, s[14:15]
	s_add_i32 m0, s19, 0xa100
	s_nop 0
	global_load_lds_dwordx4 v127, s[14:15]
	s_add_u32 s12, s12, 0x80
	s_addc_u32 s13, s13, 0
	s_add_u32 s14, s14, 0x80
	s_addc_u32 s15, s15, 0
	s_add_i32 m0, s19, 0xc100
	s_nop 0
	global_load_lds_dwordx4 v124, s[12:13]
	s_add_i32 m0, s19, 0xe100
	s_nop 0
	global_load_lds_dwordx4 v125, s[12:13]
	s_add_i32 m0, s19, 0x10100
	s_nop 0
	global_load_lds_dwordx4 v124, s[14:15]
	s_add_i32 m0, s19, 0x12100
	s_nop 0
	global_load_lds_dwordx4 v125, s[14:15]
	s_add_i32 m0, s19, 0x14100
	s_nop 0
	global_load_lds_dwordx4 v126, s[14:15]
	s_add_i32 m0, s19, 0x16100
	s_nop 0
	global_load_lds_dwordx4 v127, s[14:15]
	s_add_u32 s12, s12, 0x80
	s_addc_u32 s13, s13, 0
	s_add_u32 s14, s14, 0x80
	s_addc_u32 s15, s15, 0
	global_load_dwordx4 v[64:67], v[64:65], off
	global_load_dwordx4 v[128:131], v216, s[26:27]
	global_load_dwordx4 v[132:135], v217, s[26:27]
	global_load_dwordx4 v[136:139], v218, s[26:27]
	global_load_dwordx4 v[140:143], v219, s[26:27]
	global_load_dwordx4 v[144:147], v220, s[26:27]
	global_load_dwordx4 v[148:151], v221, s[26:27]
	global_load_dwordx4 v[152:155], v222, s[26:27]
	global_load_dwordx4 v[156:159], v223, s[26:27]
	global_load_dwordx4 v[160:163], v216, s[8:9]
	global_load_dwordx4 v[164:167], v217, s[8:9]
	global_load_dwordx4 v[168:171], v218, s[8:9]
	global_load_dwordx4 v[172:175], v219, s[8:9]
	global_load_dwordx4 v[176:179], v220, s[8:9]
	global_load_dwordx4 v[180:183], v221, s[8:9]
	global_load_dwordx4 v[190:193], v222, s[8:9]
	global_load_dwordx4 v[194:197], v223, s[8:9]
	v_mov_b32_e32 v48, 0
	v_mov_b32_e32 v49, 0
	v_mov_b32_e32 v50, 0
	v_mov_b32_e32 v51, 0
	v_mov_b32_e32 v52, 0
	v_mov_b32_e32 v53, 0
	v_mov_b32_e32 v54, 0
	v_mov_b32_e32 v55, 0
	v_mov_b32_e32 v56, 0
	v_mov_b32_e32 v57, 0
	v_mov_b32_e32 v58, 0
	v_mov_b32_e32 v59, 0
	v_mov_b32_e32 v60, 0
	v_mov_b32_e32 v61, 0
	v_mov_b32_e32 v62, 0
	v_mov_b32_e32 v63, 0
	v_mov_b32_e32 v32, 0
	v_mov_b32_e32 v33, 0
	v_mov_b32_e32 v34, 0
	v_mov_b32_e32 v35, 0
	v_mov_b32_e32 v36, 0
	v_mov_b32_e32 v37, 0
	v_mov_b32_e32 v38, 0
	v_mov_b32_e32 v39, 0
	v_mov_b32_e32 v40, 0
	v_mov_b32_e32 v41, 0
	v_mov_b32_e32 v42, 0
	v_mov_b32_e32 v43, 0
	v_mov_b32_e32 v44, 0
	v_mov_b32_e32 v45, 0
	v_mov_b32_e32 v46, 0
	v_mov_b32_e32 v47, 0
	v_mov_b32_e32 v16, 0
	v_mov_b32_e32 v17, 0
	v_mov_b32_e32 v18, 0
	v_mov_b32_e32 v19, 0
	v_mov_b32_e32 v20, 0
	v_mov_b32_e32 v21, 0
	v_mov_b32_e32 v22, 0
	v_mov_b32_e32 v23, 0
	v_mov_b32_e32 v24, 0
	v_mov_b32_e32 v25, 0
	v_mov_b32_e32 v26, 0
	v_mov_b32_e32 v27, 0
	v_mov_b32_e32 v28, 0
	v_mov_b32_e32 v29, 0
	v_mov_b32_e32 v30, 0
	v_mov_b32_e32 v31, 0
	v_mov_b32_e32 v0, 0
	v_mov_b32_e32 v1, 0
	v_mov_b32_e32 v2, 0
	v_mov_b32_e32 v3, 0
	v_mov_b32_e32 v4, 0
	v_mov_b32_e32 v5, 0
	v_mov_b32_e32 v6, 0
	v_mov_b32_e32 v7, 0
	v_mov_b32_e32 v8, 0
	v_mov_b32_e32 v9, 0
	v_mov_b32_e32 v10, 0
	v_mov_b32_e32 v11, 0
	v_mov_b32_e32 v12, 0
	v_mov_b32_e32 v13, 0
	v_mov_b32_e32 v14, 0
	v_mov_b32_e32 v15, 0
	s_movk_i32 s21, 0x100
	v_add3_u32 v224, s21, v118, v211
	v_add3_u32 v225, s21, v118, v212
	v_add3_u32 v226, s21, v118, v213
	v_add3_u32 v227, s21, v118, v214
	s_movk_i32 s21, 0x4100
	v_add3_u32 v228, s21, v119, v211
	v_add3_u32 v229, s21, v119, v212
	v_add3_u32 v230, s21, v119, v213
	v_add3_u32 v231, s21, v119, v214
	s_mov_b32 s21, 0x1b800
	v_add_u32_e32 v232, s21, v224
	v_add_u32_e32 v236, s21, v228
	v_add_u32_e32 v233, s21, v225
	v_add_u32_e32 v237, s21, v229
	v_add_u32_e32 v234, s21, v226
	v_add_u32_e32 v238, s21, v230
	v_add_u32_e32 v235, s21, v227
	v_add_u32_e32 v239, s21, v231
	s_waitcnt vmcnt(23)
	s_barrier
	ds_read_b128 v[84:87], v224
	ds_read_b128 v[92:95], v228
	ds_read_b128 v[96:99], v228 offset:4096
	ds_read_b128 v[88:91], v224 offset:4096
.Lg2_loop:
	s_add_i32 m0, s19, 0x1b900
	s_nop 0
	global_load_lds_dwordx4 v124, s[12:13]
	s_add_i32 m0, s19, 0x1d900
	s_nop 0
	global_load_lds_dwordx4 v125, s[12:13]
	s_add_i32 m0, s19, 0x1f900
	s_nop 0
	global_load_lds_dwordx4 v124, s[14:15]
	s_add_i32 m0, s19, 0x21900
	s_nop 0
	global_load_lds_dwordx4 v125, s[14:15]
	s_add_i32 m0, s19, 0x23900
	s_nop 0
	global_load_lds_dwordx4 v126, s[14:15]
	s_add_i32 m0, s19, 0x25900
	s_nop 0
	global_load_lds_dwordx4 v127, s[14:15]
	s_add_u32 s12, s12, 0x80
	s_addc_u32 s13, s13, 0
	s_add_u32 s14, s14, 0x80
	s_addc_u32 s15, s15, 0
	ds_read_b128 v[102:105], v225
	ds_read_b128 v[110:113], v229
	ds_read_b128 v[114:117], v229 offset:4096
	ds_read_b128 v[106:109], v225 offset:4096
	s_setprio 1
	s_waitcnt lgkmcnt(6)
	v_mfma_f32_32x32x16_bf16 v[48:63], v[84:87], v[92:95], v[48:63]
	s_waitcnt lgkmcnt(5)
	v_mfma_f32_32x32x16_bf16 v[32:47], v[84:87], v[96:99], v[32:47]
	s_waitcnt lgkmcnt(4)
	v_mfma_f32_32x32x16_bf16 v[16:31], v[88:91], v[92:95], v[16:31]
	v_mfma_f32_32x32x16_bf16 v[0:15], v[88:91], v[96:99], v[0:15]
	s_setprio 0
	ds_read_b128 v[84:87], v226
	ds_read_b128 v[92:95], v230
	ds_read_b128 v[96:99], v230 offset:4096
	ds_read_b128 v[88:91], v226 offset:4096
	s_setprio 1
	s_waitcnt lgkmcnt(6)
	v_mfma_f32_32x32x16_bf16 v[48:63], v[102:105], v[110:113], v[48:63]
	s_waitcnt lgkmcnt(5)
	v_mfma_f32_32x32x16_bf16 v[32:47], v[102:105], v[114:117], v[32:47]
	s_waitcnt lgkmcnt(4)
	v_mfma_f32_32x32x16_bf16 v[16:31], v[106:109], v[110:113], v[16:31]
	v_mfma_f32_32x32x16_bf16 v[0:15], v[106:109], v[114:117], v[0:15]
	s_setprio 0
	ds_read_b128 v[102:105], v227
	ds_read_b128 v[110:113], v231
	ds_read_b128 v[114:117], v231 offset:4096
	ds_read_b128 v[106:109], v227 offset:4096
	s_setprio 1
	s_waitcnt lgkmcnt(6)
	v_mfma_f32_32x32x16_bf16 v[48:63], v[84:87], v[92:95], v[48:63]
	s_waitcnt lgkmcnt(5)
	v_mfma_f32_32x32x16_bf16 v[32:47], v[84:87], v[96:99], v[32:47]
	s_waitcnt lgkmcnt(4)
	v_mfma_f32_32x32x16_bf16 v[16:31], v[88:91], v[92:95], v[16:31]
	v_mfma_f32_32x32x16_bf16 v[0:15], v[88:91], v[96:99], v[0:15]
	s_setprio 0
	s_waitcnt lgkmcnt(0)
	s_waitcnt vmcnt(23)
	s_barrier
	ds_read_b128 v[84:87], v224 offset:49152
	ds_read_b128 v[92:95], v228 offset:49152
	ds_read_b128 v[96:99], v228 offset:53248
	ds_read_b128 v[88:91], v224 offset:53248
	s_setprio 1
	v_mfma_f32_32x32x16_bf16 v[48:63], v[102:105], v[110:113], v[48:63]
	v_mfma_f32_32x32x16_bf16 v[32:47], v[102:105], v[114:117], v[32:47]
	v_mfma_f32_32x32x16_bf16 v[16:31], v[106:109], v[110:113], v[16:31]
	v_mfma_f32_32x32x16_bf16 v[0:15], v[106:109], v[114:117], v[0:15]
	s_setprio 0
	s_add_i32 m0, s19, 0x100
	s_nop 0
	global_load_lds_dwordx4 v124, s[12:13]
	s_add_i32 m0, s19, 0x2100
	s_nop 0
	global_load_lds_dwordx4 v125, s[12:13]
	s_add_i32 m0, s19, 0x4100
	s_nop 0
	global_load_lds_dwordx4 v124, s[14:15]
	s_add_i32 m0, s19, 0x6100
	s_nop 0
	global_load_lds_dwordx4 v125, s[14:15]
	s_add_i32 m0, s19, 0x8100
	s_nop 0
	global_load_lds_dwordx4 v126, s[14:15]
	s_add_i32 m0, s19, 0xa100
	s_nop 0
	global_load_lds_dwordx4 v127, s[14:15]
	s_add_u32 s12, s12, 0x80
	s_addc_u32 s13, s13, 0
	s_add_u32 s14, s14, 0x80
	s_addc_u32 s15, s15, 0
	ds_read_b128 v[102:105], v225 offset:49152
	ds_read_b128 v[110:113], v229 offset:49152
	ds_read_b128 v[114:117], v229 offset:53248
	ds_read_b128 v[106:109], v225 offset:53248
	s_setprio 1
	s_waitcnt lgkmcnt(6)
	v_mfma_f32_32x32x16_bf16 v[48:63], v[84:87], v[92:95], v[48:63]
	s_waitcnt lgkmcnt(5)
	v_mfma_f32_32x32x16_bf16 v[32:47], v[84:87], v[96:99], v[32:47]
	s_waitcnt lgkmcnt(4)
	v_mfma_f32_32x32x16_bf16 v[16:31], v[88:91], v[92:95], v[16:31]
	v_mfma_f32_32x32x16_bf16 v[0:15], v[88:91], v[96:99], v[0:15]
	s_setprio 0
	ds_read_b128 v[84:87], v226 offset:49152
	ds_read_b128 v[92:95], v230 offset:49152
	ds_read_b128 v[96:99], v230 offset:53248
	ds_read_b128 v[88:91], v226 offset:53248
	s_setprio 1
	s_waitcnt lgkmcnt(6)
	v_mfma_f32_32x32x16_bf16 v[48:63], v[102:105], v[110:113], v[48:63]
	s_waitcnt lgkmcnt(5)
	v_mfma_f32_32x32x16_bf16 v[32:47], v[102:105], v[114:117], v[32:47]
	s_waitcnt lgkmcnt(4)
	v_mfma_f32_32x32x16_bf16 v[16:31], v[106:109], v[110:113], v[16:31]
	v_mfma_f32_32x32x16_bf16 v[0:15], v[106:109], v[114:117], v[0:15]
	s_setprio 0
	ds_read_b128 v[102:105], v227 offset:49152
	ds_read_b128 v[110:113], v231 offset:49152
	ds_read_b128 v[114:117], v231 offset:53248
	ds_read_b128 v[106:109], v227 offset:53248
	s_setprio 1
	s_waitcnt lgkmcnt(6)
	v_mfma_f32_32x32x16_bf16 v[48:63], v[84:87], v[92:95], v[48:63]
	s_waitcnt lgkmcnt(5)
	v_mfma_f32_32x32x16_bf16 v[32:47], v[84:87], v[96:99], v[32:47]
	s_waitcnt lgkmcnt(4)
	v_mfma_f32_32x32x16_bf16 v[16:31], v[88:91], v[92:95], v[16:31]
	v_mfma_f32_32x32x16_bf16 v[0:15], v[88:91], v[96:99], v[0:15]
	s_setprio 0
	s_waitcnt lgkmcnt(0)
	s_waitcnt vmcnt(6)
	s_barrier
	ds_read_b128 v[84:87], v232
	ds_read_b128 v[92:95], v236
	ds_read_b128 v[96:99], v236 offset:4096
	ds_read_b128 v[88:91], v232 offset:4096
	s_setprio 1
	v_mfma_f32_32x32x16_bf16 v[48:63], v[102:105], v[110:113], v[48:63]
	v_mfma_f32_32x32x16_bf16 v[32:47], v[102:105], v[114:117], v[32:47]
	v_mfma_f32_32x32x16_bf16 v[16:31], v[106:109], v[110:113], v[16:31]
	v_mfma_f32_32x32x16_bf16 v[0:15], v[106:109], v[114:117], v[0:15]
	s_setprio 0
	s_add_i32 m0, s19, 0xc100
	s_nop 0
	global_load_lds_dwordx4 v124, s[12:13]
	s_add_i32 m0, s19, 0xe100
	s_nop 0
	global_load_lds_dwordx4 v125, s[12:13]
	s_add_i32 m0, s19, 0x10100
	s_nop 0
	global_load_lds_dwordx4 v124, s[14:15]
	s_add_i32 m0, s19, 0x12100
	s_nop 0
	global_load_lds_dwordx4 v125, s[14:15]
	s_add_i32 m0, s19, 0x14100
	s_nop 0
	global_load_lds_dwordx4 v126, s[14:15]
	s_add_i32 m0, s19, 0x16100
	s_nop 0
	global_load_lds_dwordx4 v127, s[14:15]
	s_add_u32 s12, s12, 0x80
	s_addc_u32 s13, s13, 0
	s_add_u32 s14, s14, 0x80
	s_addc_u32 s15, s15, 0
	ds_read_b128 v[102:105], v233
	ds_read_b128 v[110:113], v237
	ds_read_b128 v[114:117], v237 offset:4096
	ds_read_b128 v[106:109], v233 offset:4096
	s_setprio 1
	s_waitcnt lgkmcnt(6)
	v_mfma_f32_32x32x16_bf16 v[48:63], v[84:87], v[92:95], v[48:63]
	s_waitcnt lgkmcnt(5)
	v_mfma_f32_32x32x16_bf16 v[32:47], v[84:87], v[96:99], v[32:47]
	s_waitcnt lgkmcnt(4)
	v_mfma_f32_32x32x16_bf16 v[16:31], v[88:91], v[92:95], v[16:31]
	v_mfma_f32_32x32x16_bf16 v[0:15], v[88:91], v[96:99], v[0:15]
	s_setprio 0
	ds_read_b128 v[84:87], v234
	ds_read_b128 v[92:95], v238
	ds_read_b128 v[96:99], v238 offset:4096
	ds_read_b128 v[88:91], v234 offset:4096
	s_setprio 1
	s_waitcnt lgkmcnt(6)
	v_mfma_f32_32x32x16_bf16 v[48:63], v[102:105], v[110:113], v[48:63]
	s_waitcnt lgkmcnt(5)
	v_mfma_f32_32x32x16_bf16 v[32:47], v[102:105], v[114:117], v[32:47]
	s_waitcnt lgkmcnt(4)
	v_mfma_f32_32x32x16_bf16 v[16:31], v[106:109], v[110:113], v[16:31]
	v_mfma_f32_32x32x16_bf16 v[0:15], v[106:109], v[114:117], v[0:15]
	s_setprio 0
	ds_read_b128 v[102:105], v235
	ds_read_b128 v[110:113], v239
	ds_read_b128 v[114:117], v239 offset:4096
	ds_read_b128 v[106:109], v235 offset:4096
	s_setprio 1
	s_waitcnt lgkmcnt(6)
	v_mfma_f32_32x32x16_bf16 v[48:63], v[84:87], v[92:95], v[48:63]
	s_waitcnt lgkmcnt(5)
	v_mfma_f32_32x32x16_bf16 v[32:47], v[84:87], v[96:99], v[32:47]
	s_waitcnt lgkmcnt(4)
	v_mfma_f32_32x32x16_bf16 v[16:31], v[88:91], v[92:95], v[16:31]
	v_mfma_f32_32x32x16_bf16 v[0:15], v[88:91], v[96:99], v[0:15]
	s_setprio 0
	s_waitcnt lgkmcnt(0)
	s_waitcnt vmcnt(6)
	s_barrier
	ds_read_b128 v[84:87], v224
	ds_read_b128 v[92:95], v228
	ds_read_b128 v[96:99], v228 offset:4096
	ds_read_b128 v[88:91], v224 offset:4096
	s_setprio 1
	v_mfma_f32_32x32x16_bf16 v[48:63], v[102:105], v[110:113], v[48:63]
	v_mfma_f32_32x32x16_bf16 v[32:47], v[102:105], v[114:117], v[32:47]
	v_mfma_f32_32x32x16_bf16 v[16:31], v[106:109], v[110:113], v[16:31]
	v_mfma_f32_32x32x16_bf16 v[0:15], v[106:109], v[114:117], v[0:15]
	s_setprio 0
	s_add_i32 m0, s19, 0x1b900
	s_nop 0
	global_load_lds_dwordx4 v124, s[12:13]
	s_add_i32 m0, s19, 0x1d900
	s_nop 0
	global_load_lds_dwordx4 v125, s[12:13]
	s_add_i32 m0, s19, 0x1f900
	s_nop 0
	global_load_lds_dwordx4 v124, s[14:15]
	s_add_i32 m0, s19, 0x21900
	s_nop 0
	global_load_lds_dwordx4 v125, s[14:15]
	s_add_i32 m0, s19, 0x23900
	s_nop 0
	global_load_lds_dwordx4 v126, s[14:15]
	s_add_i32 m0, s19, 0x25900
	s_nop 0
	global_load_lds_dwordx4 v127, s[14:15]
	s_add_u32 s12, s12, 0x80
	s_addc_u32 s13, s13, 0
	s_add_u32 s14, s14, 0x80
	s_addc_u32 s15, s15, 0
	ds_read_b128 v[102:105], v225
	ds_read_b128 v[110:113], v229
	ds_read_b128 v[114:117], v229 offset:4096
	ds_read_b128 v[106:109], v225 offset:4096
	s_setprio 1
	s_waitcnt lgkmcnt(6)
	v_mfma_f32_32x32x16_bf16 v[48:63], v[84:87], v[92:95], v[48:63]
	s_waitcnt lgkmcnt(5)
	v_mfma_f32_32x32x16_bf16 v[32:47], v[84:87], v[96:99], v[32:47]
	s_waitcnt lgkmcnt(4)
	v_mfma_f32_32x32x16_bf16 v[16:31], v[88:91], v[92:95], v[16:31]
	v_mfma_f32_32x32x16_bf16 v[0:15], v[88:91], v[96:99], v[0:15]
	s_setprio 0
	ds_read_b128 v[84:87], v226
	ds_read_b128 v[92:95], v230
	ds_read_b128 v[96:99], v230 offset:4096
	ds_read_b128 v[88:91], v226 offset:4096
	s_setprio 1
	s_waitcnt lgkmcnt(6)
	v_mfma_f32_32x32x16_bf16 v[48:63], v[102:105], v[110:113], v[48:63]
	s_waitcnt lgkmcnt(5)
	v_mfma_f32_32x32x16_bf16 v[32:47], v[102:105], v[114:117], v[32:47]
	s_waitcnt lgkmcnt(4)
	v_mfma_f32_32x32x16_bf16 v[16:31], v[106:109], v[110:113], v[16:31]
	v_mfma_f32_32x32x16_bf16 v[0:15], v[106:109], v[114:117], v[0:15]
	s_setprio 0
	ds_read_b128 v[102:105], v227
	ds_read_b128 v[110:113], v231
	ds_read_b128 v[114:117], v231 offset:4096
	ds_read_b128 v[106:109], v227 offset:4096
	s_setprio 1
	s_waitcnt lgkmcnt(6)
	v_mfma_f32_32x32x16_bf16 v[48:63], v[84:87], v[92:95], v[48:63]
	s_waitcnt lgkmcnt(5)
	v_mfma_f32_32x32x16_bf16 v[32:47], v[84:87], v[96:99], v[32:47]
	s_waitcnt lgkmcnt(4)
	v_mfma_f32_32x32x16_bf16 v[16:31], v[88:91], v[92:95], v[16:31]
	v_mfma_f32_32x32x16_bf16 v[0:15], v[88:91], v[96:99], v[0:15]
	s_setprio 0
	s_waitcnt lgkmcnt(0)
	s_waitcnt vmcnt(6)
	s_barrier
	ds_read_b128 v[84:87], v224 offset:49152
	ds_read_b128 v[92:95], v228 offset:49152
	ds_read_b128 v[96:99], v228 offset:53248
	ds_read_b128 v[88:91], v224 offset:53248
	s_setprio 1
	v_mfma_f32_32x32x16_bf16 v[48:63], v[102:105], v[110:113], v[48:63]
	v_mfma_f32_32x32x16_bf16 v[32:47], v[102:105], v[114:117], v[32:47]
	v_mfma_f32_32x32x16_bf16 v[16:31], v[106:109], v[110:113], v[16:31]
	v_mfma_f32_32x32x16_bf16 v[0:15], v[106:109], v[114:117], v[0:15]
	s_setprio 0
	s_add_i32 m0, s19, 0x100
	s_nop 0
	global_load_lds_dwordx4 v124, s[12:13]
	s_add_i32 m0, s19, 0x2100
	s_nop 0
	global_load_lds_dwordx4 v125, s[12:13]
	s_add_i32 m0, s19, 0x4100
	s_nop 0
	global_load_lds_dwordx4 v124, s[14:15]
	s_add_i32 m0, s19, 0x6100
	s_nop 0
	global_load_lds_dwordx4 v125, s[14:15]
	s_add_i32 m0, s19, 0x8100
	s_nop 0
	global_load_lds_dwordx4 v126, s[14:15]
	s_add_i32 m0, s19, 0xa100
	s_nop 0
	global_load_lds_dwordx4 v127, s[14:15]
	s_add_u32 s12, s12, 0x80
	s_addc_u32 s13, s13, 0
	s_add_u32 s14, s14, 0x80
	s_addc_u32 s15, s15, 0
	ds_read_b128 v[102:105], v225 offset:49152
	ds_read_b128 v[110:113], v229 offset:49152
	ds_read_b128 v[114:117], v229 offset:53248
	ds_read_b128 v[106:109], v225 offset:53248
	s_setprio 1
	s_waitcnt lgkmcnt(6)
	v_mfma_f32_32x32x16_bf16 v[48:63], v[84:87], v[92:95], v[48:63]
	s_waitcnt lgkmcnt(5)
	v_mfma_f32_32x32x16_bf16 v[32:47], v[84:87], v[96:99], v[32:47]
	s_waitcnt lgkmcnt(4)
	v_mfma_f32_32x32x16_bf16 v[16:31], v[88:91], v[92:95], v[16:31]
	v_mfma_f32_32x32x16_bf16 v[0:15], v[88:91], v[96:99], v[0:15]
	s_setprio 0
	ds_read_b128 v[84:87], v226 offset:49152
	ds_read_b128 v[92:95], v230 offset:49152
	ds_read_b128 v[96:99], v230 offset:53248
	ds_read_b128 v[88:91], v226 offset:53248
	s_setprio 1
	s_waitcnt lgkmcnt(6)
	v_mfma_f32_32x32x16_bf16 v[48:63], v[102:105], v[110:113], v[48:63]
	s_waitcnt lgkmcnt(5)
	v_mfma_f32_32x32x16_bf16 v[32:47], v[102:105], v[114:117], v[32:47]
	s_waitcnt lgkmcnt(4)
	v_mfma_f32_32x32x16_bf16 v[16:31], v[106:109], v[110:113], v[16:31]
	v_mfma_f32_32x32x16_bf16 v[0:15], v[106:109], v[114:117], v[0:15]
	s_setprio 0
	ds_read_b128 v[102:105], v227 offset:49152
	ds_read_b128 v[110:113], v231 offset:49152
	ds_read_b128 v[114:117], v231 offset:53248
	ds_read_b128 v[106:109], v227 offset:53248
	s_setprio 1
	s_waitcnt lgkmcnt(6)
	v_mfma_f32_32x32x16_bf16 v[48:63], v[84:87], v[92:95], v[48:63]
	s_waitcnt lgkmcnt(5)
	v_mfma_f32_32x32x16_bf16 v[32:47], v[84:87], v[96:99], v[32:47]
	s_waitcnt lgkmcnt(4)
	v_mfma_f32_32x32x16_bf16 v[16:31], v[88:91], v[92:95], v[16:31]
	v_mfma_f32_32x32x16_bf16 v[0:15], v[88:91], v[96:99], v[0:15]
	s_setprio 0
	s_waitcnt lgkmcnt(0)
	s_waitcnt vmcnt(6)
	s_barrier
	ds_read_b128 v[84:87], v232
	ds_read_b128 v[92:95], v236
	ds_read_b128 v[96:99], v236 offset:4096
	ds_read_b128 v[88:91], v232 offset:4096
	s_setprio 1
	v_mfma_f32_32x32x16_bf16 v[48:63], v[102:105], v[110:113], v[48:63]
	v_mfma_f32_32x32x16_bf16 v[32:47], v[102:105], v[114:117], v[32:47]
	v_mfma_f32_32x32x16_bf16 v[16:31], v[106:109], v[110:113], v[16:31]
	v_mfma_f32_32x32x16_bf16 v[0:15], v[106:109], v[114:117], v[0:15]
	s_setprio 0
	s_add_i32 m0, s19, 0xc100
	s_nop 0
	global_load_lds_dwordx4 v124, s[12:13]
	s_add_i32 m0, s19, 0xe100
	s_nop 0
	global_load_lds_dwordx4 v125, s[12:13]
	s_add_i32 m0, s19, 0x10100
	s_nop 0
	global_load_lds_dwordx4 v124, s[14:15]
	s_add_i32 m0, s19, 0x12100
	s_nop 0
	global_load_lds_dwordx4 v125, s[14:15]
	s_add_i32 m0, s19, 0x14100
	s_nop 0
	global_load_lds_dwordx4 v126, s[14:15]
	s_add_i32 m0, s19, 0x16100
	s_nop 0
	global_load_lds_dwordx4 v127, s[14:15]
	s_add_u32 s12, s12, 0x80
	s_addc_u32 s13, s13, 0
	s_add_u32 s14, s14, 0x80
	s_addc_u32 s15, s15, 0
	ds_read_b128 v[102:105], v233
	ds_read_b128 v[110:113], v237
	ds_read_b128 v[114:117], v237 offset:4096
	ds_read_b128 v[106:109], v233 offset:4096
	s_setprio 1
	s_waitcnt lgkmcnt(6)
	v_mfma_f32_32x32x16_bf16 v[48:63], v[84:87], v[92:95], v[48:63]
	s_waitcnt lgkmcnt(5)
	v_mfma_f32_32x32x16_bf16 v[32:47], v[84:87], v[96:99], v[32:47]
	s_waitcnt lgkmcnt(4)
	v_mfma_f32_32x32x16_bf16 v[16:31], v[88:91], v[92:95], v[16:31]
	v_mfma_f32_32x32x16_bf16 v[0:15], v[88:91], v[96:99], v[0:15]
	s_setprio 0
	ds_read_b128 v[84:87], v234
	ds_read_b128 v[92:95], v238
	ds_read_b128 v[96:99], v238 offset:4096
	ds_read_b128 v[88:91], v234 offset:4096
	s_setprio 1
	s_waitcnt lgkmcnt(6)
	v_mfma_f32_32x32x16_bf16 v[48:63], v[102:105], v[110:113], v[48:63]
	s_waitcnt lgkmcnt(5)
	v_mfma_f32_32x32x16_bf16 v[32:47], v[102:105], v[114:117], v[32:47]
	s_waitcnt lgkmcnt(4)
	v_mfma_f32_32x32x16_bf16 v[16:31], v[106:109], v[110:113], v[16:31]
	v_mfma_f32_32x32x16_bf16 v[0:15], v[106:109], v[114:117], v[0:15]
	s_setprio 0
	ds_read_b128 v[102:105], v235
	ds_read_b128 v[110:113], v239
	ds_read_b128 v[114:117], v239 offset:4096
	ds_read_b128 v[106:109], v235 offset:4096
	s_setprio 1
	s_waitcnt lgkmcnt(6)
	v_mfma_f32_32x32x16_bf16 v[48:63], v[84:87], v[92:95], v[48:63]
	s_waitcnt lgkmcnt(5)
	v_mfma_f32_32x32x16_bf16 v[32:47], v[84:87], v[96:99], v[32:47]
	s_waitcnt lgkmcnt(4)
	v_mfma_f32_32x32x16_bf16 v[16:31], v[88:91], v[92:95], v[16:31]
	v_mfma_f32_32x32x16_bf16 v[0:15], v[88:91], v[96:99], v[0:15]
	s_setprio 0
	s_waitcnt lgkmcnt(0)
	s_waitcnt vmcnt(6)
	s_barrier
	ds_read_b128 v[84:87], v224
	ds_read_b128 v[92:95], v228
	ds_read_b128 v[96:99], v228 offset:4096
	ds_read_b128 v[88:91], v224 offset:4096
	s_setprio 1
	v_mfma_f32_32x32x16_bf16 v[48:63], v[102:105], v[110:113], v[48:63]
	v_mfma_f32_32x32x16_bf16 v[32:47], v[102:105], v[114:117], v[32:47]
	v_mfma_f32_32x32x16_bf16 v[16:31], v[106:109], v[110:113], v[16:31]
	v_mfma_f32_32x32x16_bf16 v[0:15], v[106:109], v[114:117], v[0:15]
	s_setprio 0
	s_add_i32 m0, s19, 0x1b900
	s_nop 0
	global_load_lds_dwordx4 v124, s[12:13]
	s_add_i32 m0, s19, 0x1d900
	s_nop 0
	global_load_lds_dwordx4 v125, s[12:13]
	s_add_i32 m0, s19, 0x1f900
	s_nop 0
	global_load_lds_dwordx4 v124, s[14:15]
	s_add_i32 m0, s19, 0x21900
	s_nop 0
	global_load_lds_dwordx4 v125, s[14:15]
	s_add_i32 m0, s19, 0x23900
	s_nop 0
	global_load_lds_dwordx4 v126, s[14:15]
	s_add_i32 m0, s19, 0x25900
	s_nop 0
	global_load_lds_dwordx4 v127, s[14:15]
	s_add_u32 s12, s12, 0x80
	s_addc_u32 s13, s13, 0
	s_add_u32 s14, s14, 0x80
	s_addc_u32 s15, s15, 0
	ds_read_b128 v[102:105], v225
	ds_read_b128 v[110:113], v229
	ds_read_b128 v[114:117], v229 offset:4096
	ds_read_b128 v[106:109], v225 offset:4096
	s_setprio 1
	s_waitcnt lgkmcnt(6)
	v_mfma_f32_32x32x16_bf16 v[48:63], v[84:87], v[92:95], v[48:63]
	s_waitcnt lgkmcnt(5)
	v_mfma_f32_32x32x16_bf16 v[32:47], v[84:87], v[96:99], v[32:47]
	s_waitcnt lgkmcnt(4)
	v_mfma_f32_32x32x16_bf16 v[16:31], v[88:91], v[92:95], v[16:31]
	v_mfma_f32_32x32x16_bf16 v[0:15], v[88:91], v[96:99], v[0:15]
	s_setprio 0
	ds_read_b128 v[84:87], v226
	ds_read_b128 v[92:95], v230
	ds_read_b128 v[96:99], v230 offset:4096
	ds_read_b128 v[88:91], v226 offset:4096
	s_setprio 1
	s_waitcnt lgkmcnt(6)
	v_mfma_f32_32x32x16_bf16 v[48:63], v[102:105], v[110:113], v[48:63]
	s_waitcnt lgkmcnt(5)
	v_mfma_f32_32x32x16_bf16 v[32:47], v[102:105], v[114:117], v[32:47]
	s_waitcnt lgkmcnt(4)
	v_mfma_f32_32x32x16_bf16 v[16:31], v[106:109], v[110:113], v[16:31]
	v_mfma_f32_32x32x16_bf16 v[0:15], v[106:109], v[114:117], v[0:15]
	s_setprio 0
	ds_read_b128 v[102:105], v227
	ds_read_b128 v[110:113], v231
	ds_read_b128 v[114:117], v231 offset:4096
	ds_read_b128 v[106:109], v227 offset:4096
	s_setprio 1
	s_waitcnt lgkmcnt(6)
	v_mfma_f32_32x32x16_bf16 v[48:63], v[84:87], v[92:95], v[48:63]
	s_waitcnt lgkmcnt(5)
	v_mfma_f32_32x32x16_bf16 v[32:47], v[84:87], v[96:99], v[32:47]
	s_waitcnt lgkmcnt(4)
	v_mfma_f32_32x32x16_bf16 v[16:31], v[88:91], v[92:95], v[16:31]
	v_mfma_f32_32x32x16_bf16 v[0:15], v[88:91], v[96:99], v[0:15]
	s_setprio 0
	s_waitcnt lgkmcnt(0)
	s_waitcnt vmcnt(6)
	s_barrier
	ds_read_b128 v[84:87], v224 offset:49152
	ds_read_b128 v[92:95], v228 offset:49152
	ds_read_b128 v[96:99], v228 offset:53248
	ds_read_b128 v[88:91], v224 offset:53248
	s_setprio 1
	v_mfma_f32_32x32x16_bf16 v[48:63], v[102:105], v[110:113], v[48:63]
	v_mfma_f32_32x32x16_bf16 v[32:47], v[102:105], v[114:117], v[32:47]
	v_mfma_f32_32x32x16_bf16 v[16:31], v[106:109], v[110:113], v[16:31]
	v_mfma_f32_32x32x16_bf16 v[0:15], v[106:109], v[114:117], v[0:15]
	s_setprio 0
	s_add_i32 m0, s19, 0x100
	s_nop 0
	global_load_lds_dwordx4 v124, s[12:13]
	s_add_i32 m0, s19, 0x2100
	s_nop 0
	global_load_lds_dwordx4 v125, s[12:13]
	s_add_i32 m0, s19, 0x4100
	s_nop 0
	global_load_lds_dwordx4 v124, s[14:15]
	s_add_i32 m0, s19, 0x6100
	s_nop 0
	global_load_lds_dwordx4 v125, s[14:15]
	s_add_i32 m0, s19, 0x8100
	s_nop 0
	global_load_lds_dwordx4 v126, s[14:15]
	s_add_i32 m0, s19, 0xa100
	s_nop 0
	global_load_lds_dwordx4 v127, s[14:15]
	s_add_u32 s12, s12, 0x80
	s_addc_u32 s13, s13, 0
	s_add_u32 s14, s14, 0x80
	s_addc_u32 s15, s15, 0
	ds_read_b128 v[102:105], v225 offset:49152
	ds_read_b128 v[110:113], v229 offset:49152
	ds_read_b128 v[114:117], v229 offset:53248
	ds_read_b128 v[106:109], v225 offset:53248
	s_setprio 1
	s_waitcnt lgkmcnt(6)
	v_mfma_f32_32x32x16_bf16 v[48:63], v[84:87], v[92:95], v[48:63]
	s_waitcnt lgkmcnt(5)
	v_mfma_f32_32x32x16_bf16 v[32:47], v[84:87], v[96:99], v[32:47]
	s_waitcnt lgkmcnt(4)
	v_mfma_f32_32x32x16_bf16 v[16:31], v[88:91], v[92:95], v[16:31]
	v_mfma_f32_32x32x16_bf16 v[0:15], v[88:91], v[96:99], v[0:15]
	s_setprio 0
	ds_read_b128 v[84:87], v226 offset:49152
	ds_read_b128 v[92:95], v230 offset:49152
	ds_read_b128 v[96:99], v230 offset:53248
	ds_read_b128 v[88:91], v226 offset:53248
	s_setprio 1
	s_waitcnt lgkmcnt(6)
	v_mfma_f32_32x32x16_bf16 v[48:63], v[102:105], v[110:113], v[48:63]
	s_waitcnt lgkmcnt(5)
	v_mfma_f32_32x32x16_bf16 v[32:47], v[102:105], v[114:117], v[32:47]
	s_waitcnt lgkmcnt(4)
	v_mfma_f32_32x32x16_bf16 v[16:31], v[106:109], v[110:113], v[16:31]
	v_mfma_f32_32x32x16_bf16 v[0:15], v[106:109], v[114:117], v[0:15]
	s_setprio 0
	ds_read_b128 v[102:105], v227 offset:49152
	ds_read_b128 v[110:113], v231 offset:49152
	ds_read_b128 v[114:117], v231 offset:53248
	ds_read_b128 v[106:109], v227 offset:53248
	s_setprio 1
	s_waitcnt lgkmcnt(6)
	v_mfma_f32_32x32x16_bf16 v[48:63], v[84:87], v[92:95], v[48:63]
	s_waitcnt lgkmcnt(5)
	v_mfma_f32_32x32x16_bf16 v[32:47], v[84:87], v[96:99], v[32:47]
	s_waitcnt lgkmcnt(4)
	v_mfma_f32_32x32x16_bf16 v[16:31], v[88:91], v[92:95], v[16:31]
	v_mfma_f32_32x32x16_bf16 v[0:15], v[88:91], v[96:99], v[0:15]
	s_setprio 0
	s_waitcnt lgkmcnt(0)
	s_waitcnt vmcnt(6)
	s_barrier
	ds_read_b128 v[84:87], v232
	ds_read_b128 v[92:95], v236
	ds_read_b128 v[96:99], v236 offset:4096
	ds_read_b128 v[88:91], v232 offset:4096
	s_setprio 1
	v_mfma_f32_32x32x16_bf16 v[48:63], v[102:105], v[110:113], v[48:63]
	v_mfma_f32_32x32x16_bf16 v[32:47], v[102:105], v[114:117], v[32:47]
	v_mfma_f32_32x32x16_bf16 v[16:31], v[106:109], v[110:113], v[16:31]
	v_mfma_f32_32x32x16_bf16 v[0:15], v[106:109], v[114:117], v[0:15]
	s_setprio 0
	s_add_i32 m0, s19, 0xc100
	s_nop 0
	global_load_lds_dwordx4 v124, s[12:13]
	s_add_i32 m0, s19, 0xe100
	s_nop 0
	global_load_lds_dwordx4 v125, s[12:13]
	s_add_i32 m0, s19, 0x10100
	s_nop 0
	global_load_lds_dwordx4 v124, s[14:15]
	s_add_i32 m0, s19, 0x12100
	s_nop 0
	global_load_lds_dwordx4 v125, s[14:15]
	s_add_i32 m0, s19, 0x14100
	s_nop 0
	global_load_lds_dwordx4 v126, s[14:15]
	s_add_i32 m0, s19, 0x16100
	s_nop 0
	global_load_lds_dwordx4 v127, s[14:15]
	s_add_u32 s12, s12, 0x80
	s_addc_u32 s13, s13, 0
	s_add_u32 s14, s14, 0x80
	s_addc_u32 s15, s15, 0
	ds_read_b128 v[102:105], v233
	ds_read_b128 v[110:113], v237
	ds_read_b128 v[114:117], v237 offset:4096
	ds_read_b128 v[106:109], v233 offset:4096
	s_setprio 1
	s_waitcnt lgkmcnt(6)
	v_mfma_f32_32x32x16_bf16 v[48:63], v[84:87], v[92:95], v[48:63]
	s_waitcnt lgkmcnt(5)
	v_mfma_f32_32x32x16_bf16 v[32:47], v[84:87], v[96:99], v[32:47]
	s_waitcnt lgkmcnt(4)
	v_mfma_f32_32x32x16_bf16 v[16:31], v[88:91], v[92:95], v[16:31]
	v_mfma_f32_32x32x16_bf16 v[0:15], v[88:91], v[96:99], v[0:15]
	s_setprio 0
	ds_read_b128 v[84:87], v234
	ds_read_b128 v[92:95], v238
	ds_read_b128 v[96:99], v238 offset:4096
	ds_read_b128 v[88:91], v234 offset:4096
	s_setprio 1
	s_waitcnt lgkmcnt(6)
	v_mfma_f32_32x32x16_bf16 v[48:63], v[102:105], v[110:113], v[48:63]
	s_waitcnt lgkmcnt(5)
	v_mfma_f32_32x32x16_bf16 v[32:47], v[102:105], v[114:117], v[32:47]
	s_waitcnt lgkmcnt(4)
	v_mfma_f32_32x32x16_bf16 v[16:31], v[106:109], v[110:113], v[16:31]
	v_mfma_f32_32x32x16_bf16 v[0:15], v[106:109], v[114:117], v[0:15]
	s_setprio 0
	ds_read_b128 v[102:105], v235
	ds_read_b128 v[110:113], v239
	ds_read_b128 v[114:117], v239 offset:4096
	ds_read_b128 v[106:109], v235 offset:4096
	s_setprio 1
	s_waitcnt lgkmcnt(6)
	v_mfma_f32_32x32x16_bf16 v[48:63], v[84:87], v[92:95], v[48:63]
	s_waitcnt lgkmcnt(5)
	v_mfma_f32_32x32x16_bf16 v[32:47], v[84:87], v[96:99], v[32:47]
	s_waitcnt lgkmcnt(4)
	v_mfma_f32_32x32x16_bf16 v[16:31], v[88:91], v[92:95], v[16:31]
	v_mfma_f32_32x32x16_bf16 v[0:15], v[88:91], v[96:99], v[0:15]
	s_setprio 0
	s_waitcnt lgkmcnt(0)
	s_waitcnt vmcnt(6)
	s_barrier
	ds_read_b128 v[84:87], v224
	ds_read_b128 v[92:95], v228
	ds_read_b128 v[96:99], v228 offset:4096
	ds_read_b128 v[88:91], v224 offset:4096
	s_setprio 1
	v_mfma_f32_32x32x16_bf16 v[48:63], v[102:105], v[110:113], v[48:63]
	v_mfma_f32_32x32x16_bf16 v[32:47], v[102:105], v[114:117], v[32:47]
	v_mfma_f32_32x32x16_bf16 v[16:31], v[106:109], v[110:113], v[16:31]
	v_mfma_f32_32x32x16_bf16 v[0:15], v[106:109], v[114:117], v[0:15]
	s_setprio 0
	s_add_i32 m0, s19, 0x1b900
	s_nop 0
	global_load_lds_dwordx4 v124, s[12:13]
	s_add_i32 m0, s19, 0x1d900
	s_nop 0
	global_load_lds_dwordx4 v125, s[12:13]
	s_add_i32 m0, s19, 0x1f900
	s_nop 0
	global_load_lds_dwordx4 v124, s[14:15]
	s_add_i32 m0, s19, 0x21900
	s_nop 0
	global_load_lds_dwordx4 v125, s[14:15]
	s_add_i32 m0, s19, 0x23900
	s_nop 0
	global_load_lds_dwordx4 v126, s[14:15]
	s_add_i32 m0, s19, 0x25900
	s_nop 0
	global_load_lds_dwordx4 v127, s[14:15]
	s_add_u32 s12, s12, 0x80
	s_addc_u32 s13, s13, 0
	s_add_u32 s14, s14, 0x80
	s_addc_u32 s15, s15, 0
	ds_read_b128 v[102:105], v225
	ds_read_b128 v[110:113], v229
	ds_read_b128 v[114:117], v229 offset:4096
	ds_read_b128 v[106:109], v225 offset:4096
	s_setprio 1
	s_waitcnt lgkmcnt(6)
	v_mfma_f32_32x32x16_bf16 v[48:63], v[84:87], v[92:95], v[48:63]
	s_waitcnt lgkmcnt(5)
	v_mfma_f32_32x32x16_bf16 v[32:47], v[84:87], v[96:99], v[32:47]
	s_waitcnt lgkmcnt(4)
	v_mfma_f32_32x32x16_bf16 v[16:31], v[88:91], v[92:95], v[16:31]
	v_mfma_f32_32x32x16_bf16 v[0:15], v[88:91], v[96:99], v[0:15]
	s_setprio 0
	ds_read_b128 v[84:87], v226
	ds_read_b128 v[92:95], v230
	ds_read_b128 v[96:99], v230 offset:4096
	ds_read_b128 v[88:91], v226 offset:4096
	s_setprio 1
	s_waitcnt lgkmcnt(6)
	v_mfma_f32_32x32x16_bf16 v[48:63], v[102:105], v[110:113], v[48:63]
	s_waitcnt lgkmcnt(5)
	v_mfma_f32_32x32x16_bf16 v[32:47], v[102:105], v[114:117], v[32:47]
	s_waitcnt lgkmcnt(4)
	v_mfma_f32_32x32x16_bf16 v[16:31], v[106:109], v[110:113], v[16:31]
	v_mfma_f32_32x32x16_bf16 v[0:15], v[106:109], v[114:117], v[0:15]
	s_setprio 0
	ds_read_b128 v[102:105], v227
	ds_read_b128 v[110:113], v231
	ds_read_b128 v[114:117], v231 offset:4096
	ds_read_b128 v[106:109], v227 offset:4096
	s_setprio 1
	s_waitcnt lgkmcnt(6)
	v_mfma_f32_32x32x16_bf16 v[48:63], v[84:87], v[92:95], v[48:63]
	s_waitcnt lgkmcnt(5)
	v_mfma_f32_32x32x16_bf16 v[32:47], v[84:87], v[96:99], v[32:47]
	s_waitcnt lgkmcnt(4)
	v_mfma_f32_32x32x16_bf16 v[16:31], v[88:91], v[92:95], v[16:31]
	v_mfma_f32_32x32x16_bf16 v[0:15], v[88:91], v[96:99], v[0:15]
	s_setprio 0
	s_waitcnt lgkmcnt(0)
	s_waitcnt vmcnt(6)
	s_barrier
	ds_read_b128 v[84:87], v224 offset:49152
	ds_read_b128 v[92:95], v228 offset:49152
	ds_read_b128 v[96:99], v228 offset:53248
	ds_read_b128 v[88:91], v224 offset:53248
	s_setprio 1
	v_mfma_f32_32x32x16_bf16 v[48:63], v[102:105], v[110:113], v[48:63]
	v_mfma_f32_32x32x16_bf16 v[32:47], v[102:105], v[114:117], v[32:47]
	v_mfma_f32_32x32x16_bf16 v[16:31], v[106:109], v[110:113], v[16:31]
	v_mfma_f32_32x32x16_bf16 v[0:15], v[106:109], v[114:117], v[0:15]
	s_setprio 0
	s_add_i32 m0, s19, 0x100
	s_nop 0
	global_load_lds_dwordx4 v124, s[12:13]
	s_add_i32 m0, s19, 0x2100
	s_nop 0
	global_load_lds_dwordx4 v125, s[12:13]
	s_add_i32 m0, s19, 0x4100
	s_nop 0
	global_load_lds_dwordx4 v124, s[14:15]
	s_add_i32 m0, s19, 0x6100
	s_nop 0
	global_load_lds_dwordx4 v125, s[14:15]
	s_add_i32 m0, s19, 0x8100
	s_nop 0
	global_load_lds_dwordx4 v126, s[14:15]
	s_add_i32 m0, s19, 0xa100
	s_nop 0
	global_load_lds_dwordx4 v127, s[14:15]
	s_add_u32 s12, s12, 0x80
	s_addc_u32 s13, s13, 0
	s_add_u32 s14, s14, 0x80
	s_addc_u32 s15, s15, 0
	ds_read_b128 v[102:105], v225 offset:49152
	ds_read_b128 v[110:113], v229 offset:49152
	ds_read_b128 v[114:117], v229 offset:53248
	ds_read_b128 v[106:109], v225 offset:53248
	s_setprio 1
	s_waitcnt lgkmcnt(6)
	v_mfma_f32_32x32x16_bf16 v[48:63], v[84:87], v[92:95], v[48:63]
	s_waitcnt lgkmcnt(5)
	v_mfma_f32_32x32x16_bf16 v[32:47], v[84:87], v[96:99], v[32:47]
	s_waitcnt lgkmcnt(4)
	v_mfma_f32_32x32x16_bf16 v[16:31], v[88:91], v[92:95], v[16:31]
	v_mfma_f32_32x32x16_bf16 v[0:15], v[88:91], v[96:99], v[0:15]
	s_setprio 0
	ds_read_b128 v[84:87], v226 offset:49152
	ds_read_b128 v[92:95], v230 offset:49152
	ds_read_b128 v[96:99], v230 offset:53248
	ds_read_b128 v[88:91], v226 offset:53248
	s_setprio 1
	s_waitcnt lgkmcnt(6)
	v_mfma_f32_32x32x16_bf16 v[48:63], v[102:105], v[110:113], v[48:63]
	s_waitcnt lgkmcnt(5)
	v_mfma_f32_32x32x16_bf16 v[32:47], v[102:105], v[114:117], v[32:47]
	s_waitcnt lgkmcnt(4)
	v_mfma_f32_32x32x16_bf16 v[16:31], v[106:109], v[110:113], v[16:31]
	v_mfma_f32_32x32x16_bf16 v[0:15], v[106:109], v[114:117], v[0:15]
	s_setprio 0
	ds_read_b128 v[102:105], v227 offset:49152
	ds_read_b128 v[110:113], v231 offset:49152
	ds_read_b128 v[114:117], v231 offset:53248
	ds_read_b128 v[106:109], v227 offset:53248
	s_setprio 1
	s_waitcnt lgkmcnt(6)
	v_mfma_f32_32x32x16_bf16 v[48:63], v[84:87], v[92:95], v[48:63]
	s_waitcnt lgkmcnt(5)
	v_mfma_f32_32x32x16_bf16 v[32:47], v[84:87], v[96:99], v[32:47]
	s_waitcnt lgkmcnt(4)
	v_mfma_f32_32x32x16_bf16 v[16:31], v[88:91], v[92:95], v[16:31]
	v_mfma_f32_32x32x16_bf16 v[0:15], v[88:91], v[96:99], v[0:15]
	s_setprio 0
	s_waitcnt lgkmcnt(0)
	s_waitcnt vmcnt(6)
	s_barrier
	ds_read_b128 v[84:87], v232
	ds_read_b128 v[92:95], v236
	ds_read_b128 v[96:99], v236 offset:4096
	ds_read_b128 v[88:91], v232 offset:4096
	s_setprio 1
	v_mfma_f32_32x32x16_bf16 v[48:63], v[102:105], v[110:113], v[48:63]
	v_mfma_f32_32x32x16_bf16 v[32:47], v[102:105], v[114:117], v[32:47]
	v_mfma_f32_32x32x16_bf16 v[16:31], v[106:109], v[110:113], v[16:31]
	v_mfma_f32_32x32x16_bf16 v[0:15], v[106:109], v[114:117], v[0:15]
	s_setprio 0
	s_add_i32 m0, s19, 0xc100
	s_nop 0
	global_load_lds_dwordx4 v124, s[12:13]
	s_add_i32 m0, s19, 0xe100
	s_nop 0
	global_load_lds_dwordx4 v125, s[12:13]
	s_add_i32 m0, s19, 0x10100
	s_nop 0
	global_load_lds_dwordx4 v124, s[14:15]
	s_add_i32 m0, s19, 0x12100
	s_nop 0
	global_load_lds_dwordx4 v125, s[14:15]
	s_add_i32 m0, s19, 0x14100
	s_nop 0
	global_load_lds_dwordx4 v126, s[14:15]
	s_add_i32 m0, s19, 0x16100
	s_nop 0
	global_load_lds_dwordx4 v127, s[14:15]
	s_add_u32 s12, s12, 0x80
	s_addc_u32 s13, s13, 0
	s_add_u32 s14, s14, 0x80
	s_addc_u32 s15, s15, 0
	ds_read_b128 v[102:105], v233
	ds_read_b128 v[110:113], v237
	ds_read_b128 v[114:117], v237 offset:4096
	ds_read_b128 v[106:109], v233 offset:4096
	s_setprio 1
	s_waitcnt lgkmcnt(6)
	v_mfma_f32_32x32x16_bf16 v[48:63], v[84:87], v[92:95], v[48:63]
	s_waitcnt lgkmcnt(5)
	v_mfma_f32_32x32x16_bf16 v[32:47], v[84:87], v[96:99], v[32:47]
	s_waitcnt lgkmcnt(4)
	v_mfma_f32_32x32x16_bf16 v[16:31], v[88:91], v[92:95], v[16:31]
	v_mfma_f32_32x32x16_bf16 v[0:15], v[88:91], v[96:99], v[0:15]
	s_setprio 0
	ds_read_b128 v[84:87], v234
	ds_read_b128 v[92:95], v238
	ds_read_b128 v[96:99], v238 offset:4096
	ds_read_b128 v[88:91], v234 offset:4096
	s_setprio 1
	s_waitcnt lgkmcnt(6)
	v_mfma_f32_32x32x16_bf16 v[48:63], v[102:105], v[110:113], v[48:63]
	s_waitcnt lgkmcnt(5)
	v_mfma_f32_32x32x16_bf16 v[32:47], v[102:105], v[114:117], v[32:47]
	s_waitcnt lgkmcnt(4)
	v_mfma_f32_32x32x16_bf16 v[16:31], v[106:109], v[110:113], v[16:31]
	v_mfma_f32_32x32x16_bf16 v[0:15], v[106:109], v[114:117], v[0:15]
	s_setprio 0
	ds_read_b128 v[102:105], v235
	ds_read_b128 v[110:113], v239
	ds_read_b128 v[114:117], v239 offset:4096
	ds_read_b128 v[106:109], v235 offset:4096
	s_setprio 1
	s_waitcnt lgkmcnt(6)
	v_mfma_f32_32x32x16_bf16 v[48:63], v[84:87], v[92:95], v[48:63]
	s_waitcnt lgkmcnt(5)
	v_mfma_f32_32x32x16_bf16 v[32:47], v[84:87], v[96:99], v[32:47]
	s_waitcnt lgkmcnt(4)
	v_mfma_f32_32x32x16_bf16 v[16:31], v[88:91], v[92:95], v[16:31]
	v_mfma_f32_32x32x16_bf16 v[0:15], v[88:91], v[96:99], v[0:15]
	s_setprio 0
	s_waitcnt lgkmcnt(0)
	s_waitcnt vmcnt(6)
	s_barrier
	ds_read_b128 v[84:87], v224
	ds_read_b128 v[92:95], v228
	ds_read_b128 v[96:99], v228 offset:4096
	ds_read_b128 v[88:91], v224 offset:4096
	s_setprio 1
	v_mfma_f32_32x32x16_bf16 v[48:63], v[102:105], v[110:113], v[48:63]
	v_mfma_f32_32x32x16_bf16 v[32:47], v[102:105], v[114:117], v[32:47]
	v_mfma_f32_32x32x16_bf16 v[16:31], v[106:109], v[110:113], v[16:31]
	v_mfma_f32_32x32x16_bf16 v[0:15], v[106:109], v[114:117], v[0:15]
	s_setprio 0
	s_add_i32 m0, s19, 0x1b900
	s_nop 0
	global_load_lds_dwordx4 v124, s[12:13]
	s_add_i32 m0, s19, 0x1d900
	s_nop 0
	global_load_lds_dwordx4 v125, s[12:13]
	s_add_i32 m0, s19, 0x1f900
	s_nop 0
	global_load_lds_dwordx4 v124, s[14:15]
	s_add_i32 m0, s19, 0x21900
	s_nop 0
	global_load_lds_dwordx4 v125, s[14:15]
	s_add_i32 m0, s19, 0x23900
	s_nop 0
	global_load_lds_dwordx4 v126, s[14:15]
	s_add_i32 m0, s19, 0x25900
	s_nop 0
	global_load_lds_dwordx4 v127, s[14:15]
	s_add_u32 s12, s12, 0x80
	s_addc_u32 s13, s13, 0
	s_add_u32 s14, s14, 0x80
	s_addc_u32 s15, s15, 0
	ds_read_b128 v[102:105], v225
	ds_read_b128 v[110:113], v229
	ds_read_b128 v[114:117], v229 offset:4096
	ds_read_b128 v[106:109], v225 offset:4096
	s_setprio 1
	s_waitcnt lgkmcnt(6)
	v_mfma_f32_32x32x16_bf16 v[48:63], v[84:87], v[92:95], v[48:63]
	s_waitcnt lgkmcnt(5)
	v_mfma_f32_32x32x16_bf16 v[32:47], v[84:87], v[96:99], v[32:47]
	s_waitcnt lgkmcnt(4)
	v_mfma_f32_32x32x16_bf16 v[16:31], v[88:91], v[92:95], v[16:31]
	v_mfma_f32_32x32x16_bf16 v[0:15], v[88:91], v[96:99], v[0:15]
	s_setprio 0
	ds_read_b128 v[84:87], v226
	ds_read_b128 v[92:95], v230
	ds_read_b128 v[96:99], v230 offset:4096
	ds_read_b128 v[88:91], v226 offset:4096
	s_setprio 1
	s_waitcnt lgkmcnt(6)
	v_mfma_f32_32x32x16_bf16 v[48:63], v[102:105], v[110:113], v[48:63]
	s_waitcnt lgkmcnt(5)
	v_mfma_f32_32x32x16_bf16 v[32:47], v[102:105], v[114:117], v[32:47]
	s_waitcnt lgkmcnt(4)
	v_mfma_f32_32x32x16_bf16 v[16:31], v[106:109], v[110:113], v[16:31]
	v_mfma_f32_32x32x16_bf16 v[0:15], v[106:109], v[114:117], v[0:15]
	s_setprio 0
	ds_read_b128 v[102:105], v227
	ds_read_b128 v[110:113], v231
	ds_read_b128 v[114:117], v231 offset:4096
	ds_read_b128 v[106:109], v227 offset:4096
	s_setprio 1
	s_waitcnt lgkmcnt(6)
	v_mfma_f32_32x32x16_bf16 v[48:63], v[84:87], v[92:95], v[48:63]
	s_waitcnt lgkmcnt(5)
	v_mfma_f32_32x32x16_bf16 v[32:47], v[84:87], v[96:99], v[32:47]
	s_waitcnt lgkmcnt(4)
	v_mfma_f32_32x32x16_bf16 v[16:31], v[88:91], v[92:95], v[16:31]
	v_mfma_f32_32x32x16_bf16 v[0:15], v[88:91], v[96:99], v[0:15]
	s_setprio 0
	s_waitcnt lgkmcnt(0)
	s_waitcnt vmcnt(6)
	s_barrier
	ds_read_b128 v[84:87], v224 offset:49152
	ds_read_b128 v[92:95], v228 offset:49152
	ds_read_b128 v[96:99], v228 offset:53248
	ds_read_b128 v[88:91], v224 offset:53248
	s_setprio 1
	v_mfma_f32_32x32x16_bf16 v[48:63], v[102:105], v[110:113], v[48:63]
	v_mfma_f32_32x32x16_bf16 v[32:47], v[102:105], v[114:117], v[32:47]
	v_mfma_f32_32x32x16_bf16 v[16:31], v[106:109], v[110:113], v[16:31]
	v_mfma_f32_32x32x16_bf16 v[0:15], v[106:109], v[114:117], v[0:15]
	s_setprio 0
	s_add_i32 m0, s19, 0x100
	s_nop 0
	global_load_lds_dwordx4 v124, s[12:13]
	s_add_i32 m0, s19, 0x2100
	s_nop 0
	global_load_lds_dwordx4 v125, s[12:13]
	s_add_i32 m0, s19, 0x4100
	s_nop 0
	global_load_lds_dwordx4 v124, s[14:15]
	s_add_i32 m0, s19, 0x6100
	s_nop 0
	global_load_lds_dwordx4 v125, s[14:15]
	s_add_i32 m0, s19, 0x8100
	s_nop 0
	global_load_lds_dwordx4 v126, s[14:15]
	s_add_i32 m0, s19, 0xa100
	s_nop 0
	global_load_lds_dwordx4 v127, s[14:15]
	s_add_u32 s12, s12, 0x80
	s_addc_u32 s13, s13, 0
	s_add_u32 s14, s14, 0x80
	s_addc_u32 s15, s15, 0
	ds_read_b128 v[102:105], v225 offset:49152
	ds_read_b128 v[110:113], v229 offset:49152
	ds_read_b128 v[114:117], v229 offset:53248
	ds_read_b128 v[106:109], v225 offset:53248
	s_setprio 1
	s_waitcnt lgkmcnt(6)
	v_mfma_f32_32x32x16_bf16 v[48:63], v[84:87], v[92:95], v[48:63]
	s_waitcnt lgkmcnt(5)
	v_mfma_f32_32x32x16_bf16 v[32:47], v[84:87], v[96:99], v[32:47]
	s_waitcnt lgkmcnt(4)
	v_mfma_f32_32x32x16_bf16 v[16:31], v[88:91], v[92:95], v[16:31]
	v_mfma_f32_32x32x16_bf16 v[0:15], v[88:91], v[96:99], v[0:15]
	s_setprio 0
	ds_read_b128 v[84:87], v226 offset:49152
	ds_read_b128 v[92:95], v230 offset:49152
	ds_read_b128 v[96:99], v230 offset:53248
	ds_read_b128 v[88:91], v226 offset:53248
	s_setprio 1
	s_waitcnt lgkmcnt(6)
	v_mfma_f32_32x32x16_bf16 v[48:63], v[102:105], v[110:113], v[48:63]
	s_waitcnt lgkmcnt(5)
	v_mfma_f32_32x32x16_bf16 v[32:47], v[102:105], v[114:117], v[32:47]
	s_waitcnt lgkmcnt(4)
	v_mfma_f32_32x32x16_bf16 v[16:31], v[106:109], v[110:113], v[16:31]
	v_mfma_f32_32x32x16_bf16 v[0:15], v[106:109], v[114:117], v[0:15]
	s_setprio 0
	ds_read_b128 v[102:105], v227 offset:49152
	ds_read_b128 v[110:113], v231 offset:49152
	ds_read_b128 v[114:117], v231 offset:53248
	ds_read_b128 v[106:109], v227 offset:53248
	s_setprio 1
	s_waitcnt lgkmcnt(6)
	v_mfma_f32_32x32x16_bf16 v[48:63], v[84:87], v[92:95], v[48:63]
	s_waitcnt lgkmcnt(5)
	v_mfma_f32_32x32x16_bf16 v[32:47], v[84:87], v[96:99], v[32:47]
	s_waitcnt lgkmcnt(4)
	v_mfma_f32_32x32x16_bf16 v[16:31], v[88:91], v[92:95], v[16:31]
	v_mfma_f32_32x32x16_bf16 v[0:15], v[88:91], v[96:99], v[0:15]
	s_setprio 0
	s_waitcnt lgkmcnt(0)
	s_waitcnt vmcnt(6)
	s_barrier
	ds_read_b128 v[84:87], v232
	ds_read_b128 v[92:95], v236
	ds_read_b128 v[96:99], v236 offset:4096
	ds_read_b128 v[88:91], v232 offset:4096
	s_setprio 1
	v_mfma_f32_32x32x16_bf16 v[48:63], v[102:105], v[110:113], v[48:63]
	v_mfma_f32_32x32x16_bf16 v[32:47], v[102:105], v[114:117], v[32:47]
	v_mfma_f32_32x32x16_bf16 v[16:31], v[106:109], v[110:113], v[16:31]
	v_mfma_f32_32x32x16_bf16 v[0:15], v[106:109], v[114:117], v[0:15]
	s_setprio 0
	ds_read_b128 v[102:105], v233
	ds_read_b128 v[110:113], v237
	ds_read_b128 v[114:117], v237 offset:4096
	ds_read_b128 v[106:109], v233 offset:4096
	s_setprio 1
	s_waitcnt lgkmcnt(6)
	v_mfma_f32_32x32x16_bf16 v[48:63], v[84:87], v[92:95], v[48:63]
	s_waitcnt lgkmcnt(5)
	v_mfma_f32_32x32x16_bf16 v[32:47], v[84:87], v[96:99], v[32:47]
	s_waitcnt lgkmcnt(4)
	v_mfma_f32_32x32x16_bf16 v[16:31], v[88:91], v[92:95], v[16:31]
	v_mfma_f32_32x32x16_bf16 v[0:15], v[88:91], v[96:99], v[0:15]
	s_setprio 0
	ds_read_b128 v[84:87], v234
	ds_read_b128 v[92:95], v238
	ds_read_b128 v[96:99], v238 offset:4096
	ds_read_b128 v[88:91], v234 offset:4096
	s_setprio 1
	s_waitcnt lgkmcnt(6)
	v_mfma_f32_32x32x16_bf16 v[48:63], v[102:105], v[110:113], v[48:63]
	s_waitcnt lgkmcnt(5)
	v_mfma_f32_32x32x16_bf16 v[32:47], v[102:105], v[114:117], v[32:47]
	s_waitcnt lgkmcnt(4)
	v_mfma_f32_32x32x16_bf16 v[16:31], v[106:109], v[110:113], v[16:31]
	v_mfma_f32_32x32x16_bf16 v[0:15], v[106:109], v[114:117], v[0:15]
	s_setprio 0
	ds_read_b128 v[102:105], v235
	ds_read_b128 v[110:113], v239
	ds_read_b128 v[114:117], v239 offset:4096
	ds_read_b128 v[106:109], v235 offset:4096
	s_setprio 1
	s_waitcnt lgkmcnt(6)
	v_mfma_f32_32x32x16_bf16 v[48:63], v[84:87], v[92:95], v[48:63]
	s_waitcnt lgkmcnt(5)
	v_mfma_f32_32x32x16_bf16 v[32:47], v[84:87], v[96:99], v[32:47]
	s_waitcnt lgkmcnt(4)
	v_mfma_f32_32x32x16_bf16 v[16:31], v[88:91], v[92:95], v[16:31]
	v_mfma_f32_32x32x16_bf16 v[0:15], v[88:91], v[96:99], v[0:15]
	s_setprio 0
	s_waitcnt lgkmcnt(0)
	s_waitcnt vmcnt(0)
	s_barrier
	ds_read_b128 v[84:87], v224
	ds_read_b128 v[92:95], v228
	ds_read_b128 v[96:99], v228 offset:4096
	ds_read_b128 v[88:91], v224 offset:4096
	s_setprio 1
	v_mfma_f32_32x32x16_bf16 v[48:63], v[102:105], v[110:113], v[48:63]
	v_mfma_f32_32x32x16_bf16 v[32:47], v[102:105], v[114:117], v[32:47]
	v_mfma_f32_32x32x16_bf16 v[16:31], v[106:109], v[110:113], v[16:31]
	v_mfma_f32_32x32x16_bf16 v[0:15], v[106:109], v[114:117], v[0:15]
	s_setprio 0
	ds_read_b128 v[102:105], v225
	ds_read_b128 v[110:113], v229
	ds_read_b128 v[114:117], v229 offset:4096
	ds_read_b128 v[106:109], v225 offset:4096
	s_setprio 1
	s_waitcnt lgkmcnt(6)
	v_mfma_f32_32x32x16_bf16 v[48:63], v[84:87], v[92:95], v[48:63]
	s_waitcnt lgkmcnt(5)
	v_mfma_f32_32x32x16_bf16 v[32:47], v[84:87], v[96:99], v[32:47]
	s_waitcnt lgkmcnt(4)
	v_mfma_f32_32x32x16_bf16 v[16:31], v[88:91], v[92:95], v[16:31]
	v_mfma_f32_32x32x16_bf16 v[0:15], v[88:91], v[96:99], v[0:15]
	s_setprio 0
	ds_read_b128 v[84:87], v226
	ds_read_b128 v[92:95], v230
	ds_read_b128 v[96:99], v230 offset:4096
	ds_read_b128 v[88:91], v226 offset:4096
	s_setprio 1
	s_waitcnt lgkmcnt(6)
	v_mfma_f32_32x32x16_bf16 v[48:63], v[102:105], v[110:113], v[48:63]
	s_waitcnt lgkmcnt(5)
	v_mfma_f32_32x32x16_bf16 v[32:47], v[102:105], v[114:117], v[32:47]
	s_waitcnt lgkmcnt(4)
	v_mfma_f32_32x32x16_bf16 v[16:31], v[106:109], v[110:113], v[16:31]
	v_mfma_f32_32x32x16_bf16 v[0:15], v[106:109], v[114:117], v[0:15]
	s_setprio 0
	ds_read_b128 v[102:105], v227
	ds_read_b128 v[110:113], v231
	ds_read_b128 v[114:117], v231 offset:4096
	ds_read_b128 v[106:109], v227 offset:4096
	s_setprio 1
	s_waitcnt lgkmcnt(6)
	v_mfma_f32_32x32x16_bf16 v[48:63], v[84:87], v[92:95], v[48:63]
	s_waitcnt lgkmcnt(5)
	v_mfma_f32_32x32x16_bf16 v[32:47], v[84:87], v[96:99], v[32:47]
	s_waitcnt lgkmcnt(4)
	v_mfma_f32_32x32x16_bf16 v[16:31], v[88:91], v[92:95], v[16:31]
	v_mfma_f32_32x32x16_bf16 v[0:15], v[88:91], v[96:99], v[0:15]
	s_setprio 0
	s_waitcnt lgkmcnt(0)
	s_waitcnt vmcnt(0)
	s_barrier
